# expert phase packed-f32 VALU ops replaced by scalar fma/mul/add pairs (pads kept)
# speedup vs baseline: 1.0015x; 1.0015x over previous
; __device__ __forceinline__ void phase_expert(const Params& p, int layer, int row0) {
;     ...
;     for (int i0 = 0; i0 < 128; i0 += 4) {
;       u32x4 ua[4]; u32x2 ub[4];
;       float gk[4];
;       int ek[4];
; #pragma unroll
;       for (int k = 0; k < 4; ++k) {
;         ek[k] = __builtin_amdgcn_readfirstlane(ex[i0 + k]);
;         gk[k] = gt[i0 + k];
;         const unsigned char* up = UB + (size_t)ek[k] * 1536;
;         ua[k] = *(const u32x4*)(up + lane * 16); ub[k] = *(const u32x2*)(up + 1024 + lane * 8);
;       }
;       float dk[4];
; #pragma unroll
;       for (int k = 0; k < 4; ++k) {
;         const u32x6 pk = {ua[k][0], ua[k][1], ua[k][2], ua[k][3], ub[k][0], ub[k][1]};
;         const f32x32 f = __builtin_amdgcn_cvt_scalef32_pk32_f32_fp6(pk, 1.0f);
;         float d0 = 0.f, d1 = 0.f;
; #pragma unroll
;         for (int j = 0; j < 32; j += 2) { d0 += f[j] * u[j]; d1 += f[j + 1] * u[j + 1]; }
;         dk[k] = d0 + d1;
;         __builtin_amdgcn_sched_barrier(0);
;       }
; #pragma unroll
;       for (int k = 0; k < 4; ++k) {
;         const unsigned char* vp = VB + (size_t)ek[k] * 1536;
;         ua[k] = *(const u32x4*)(vp + lane * 16); ub[k] = *(const u32x2*)(vp + 1024 + lane * 8);
;       }
.LBB0_1933:
	s_add_u32 s98, s50, 16
	s_addc_u32 s99, s51, 0
	s_cmp_ge_i32 s69, 0x78
	s_cselect_b32 s98, s50, s98
	s_cselect_b32 s99, s51, s99
	global_load_dwordx4 v[252:255], v139, s[98:99]
	global_load_dwordx4 v[134:137], v224, s[50:51]
	s_waitcnt vmcnt(8)
	v_cvt_scalef32_pk32_f32_fp6 v[0:31], v[226:231], 1.0
	v_fma_f32 v0, v0, v150, 0
	v_fma_f32 v1, v1, v151, 0
	s_nop 0
	v_fma_f32 v0, v2, v152, v0
	v_fma_f32 v1, v3, v153, v1
	s_nop 0
	v_fma_f32 v0, v4, v154, v0
	v_fma_f32 v1, v5, v155, v1
	s_nop 0
	v_fma_f32 v0, v6, v156, v0
	v_fma_f32 v1, v7, v157, v1
	s_nop 0
	v_fma_f32 v0, v8, v144, v0
	v_fma_f32 v1, v9, v145, v1
	s_nop 0
	v_fma_f32 v0, v10, v146, v0
	v_fma_f32 v1, v11, v147, v1
	s_nop 0
	v_fma_f32 v0, v12, v148, v0
	v_fma_f32 v1, v13, v149, v1
	s_nop 0
	v_fma_f32 v0, v14, v158, v0
	v_fma_f32 v1, v15, v159, v1
	s_nop 0
	v_fma_f32 v0, v16, v160, v0
	v_fma_f32 v1, v17, v161, v1
	s_nop 0
	v_fma_f32 v0, v18, v164, v0
	v_fma_f32 v1, v19, v165, v1
	s_nop 0
	v_fma_f32 v0, v20, v170, v0
	v_fma_f32 v1, v21, v171, v1
	s_nop 0
	v_fma_f32 v0, v22, v174, v0
	v_fma_f32 v1, v23, v175, v1
	s_nop 0
	v_fma_f32 v0, v24, v162, v0
	v_fma_f32 v1, v25, v163, v1
	s_nop 0
	v_fma_f32 v0, v26, v166, v0
	v_fma_f32 v1, v27, v167, v1
	s_nop 0
	v_fma_f32 v0, v28, v172, v0
	v_fma_f32 v1, v29, v173, v1
	s_nop 0
	v_fma_f32 v56, v30, v176, v0
	v_fma_f32 v57, v31, v177, v1
	s_waitcnt vmcnt(6)
	v_cvt_scalef32_pk32_f32_fp6 v[0:31], v[232:237], 1.0
	v_fma_f32 v0, v0, v150, 0
	v_fma_f32 v1, v1, v151, 0
	s_nop 0
	v_fma_f32 v0, v2, v152, v0
	v_fma_f32 v1, v3, v153, v1
	s_nop 0
	v_fma_f32 v0, v4, v154, v0
	v_fma_f32 v1, v5, v155, v1
	s_nop 0
	v_fma_f32 v0, v6, v156, v0
	v_fma_f32 v1, v7, v157, v1
	s_nop 0
	v_fma_f32 v0, v8, v144, v0
	v_fma_f32 v1, v9, v145, v1
	s_nop 0
	v_fma_f32 v0, v10, v146, v0
	v_fma_f32 v1, v11, v147, v1
	s_nop 0
	v_fma_f32 v0, v12, v148, v0
	v_fma_f32 v1, v13, v149, v1
	s_nop 0
	v_fma_f32 v0, v14, v158, v0
	v_fma_f32 v1, v15, v159, v1
	s_nop 0
	v_fma_f32 v0, v16, v160, v0
	v_fma_f32 v1, v17, v161, v1
	s_nop 0
	v_fma_f32 v0, v18, v164, v0
	v_fma_f32 v1, v19, v165, v1
	s_nop 0
	v_fma_f32 v0, v20, v170, v0
	v_fma_f32 v1, v21, v171, v1
	s_nop 0
	v_fma_f32 v0, v22, v174, v0
	v_fma_f32 v1, v23, v175, v1
	s_nop 0
	v_fma_f32 v0, v24, v162, v0
	v_fma_f32 v1, v25, v163, v1
	s_nop 0
	v_fma_f32 v0, v26, v166, v0
	v_fma_f32 v1, v27, v167, v1
	s_nop 0
	v_fma_f32 v0, v28, v172, v0
	v_fma_f32 v1, v29, v173, v1
	s_nop 0
	v_fma_f32 v58, v30, v176, v0
	v_fma_f32 v59, v31, v177, v1
	s_waitcnt vmcnt(4)
	v_cvt_scalef32_pk32_f32_fp6 v[0:31], v[240:245], 1.0
	v_fma_f32 v0, v0, v150, 0
	v_fma_f32 v1, v1, v151, 0
	s_nop 0
	v_fma_f32 v0, v2, v152, v0
	v_fma_f32 v1, v3, v153, v1
	s_nop 0
	v_fma_f32 v0, v4, v154, v0
	v_fma_f32 v1, v5, v155, v1
	s_nop 0
	v_fma_f32 v0, v6, v156, v0
	v_fma_f32 v1, v7, v157, v1
	s_nop 0
	v_fma_f32 v0, v8, v144, v0
	v_fma_f32 v1, v9, v145, v1
	s_nop 0
	v_fma_f32 v0, v10, v146, v0
	v_fma_f32 v1, v11, v147, v1
	s_nop 0
	v_fma_f32 v0, v12, v148, v0
	v_fma_f32 v1, v13, v149, v1
	s_nop 0
	v_fma_f32 v0, v14, v158, v0
	v_fma_f32 v1, v15, v159, v1
	s_nop 0
	v_fma_f32 v0, v16, v160, v0
	v_fma_f32 v1, v17, v161, v1
	s_nop 0
	v_fma_f32 v0, v18, v164, v0
	v_fma_f32 v1, v19, v165, v1
	s_nop 0
	v_fma_f32 v0, v20, v170, v0
	v_fma_f32 v1, v21, v171, v1
	s_nop 0
	v_fma_f32 v0, v22, v174, v0
	v_fma_f32 v1, v23, v175, v1
	s_nop 0
	v_fma_f32 v0, v24, v162, v0
	v_fma_f32 v1, v25, v163, v1
	s_nop 0
	v_fma_f32 v0, v26, v166, v0
	v_fma_f32 v1, v27, v167, v1
	s_nop 0
	v_fma_f32 v0, v28, v172, v0
	v_fma_f32 v1, v29, v173, v1
	s_nop 0
	v_fma_f32 v96, v30, v176, v0
	v_fma_f32 v97, v31, v177, v1
	s_waitcnt vmcnt(2)
	v_cvt_scalef32_pk32_f32_fp6 v[0:31], v[246:251], 1.0
	v_fma_f32 v0, v0, v150, 0
	v_fma_f32 v1, v1, v151, 0
	s_nop 0
	v_fma_f32 v0, v2, v152, v0
	v_fma_f32 v1, v3, v153, v1
	s_nop 0
	v_fma_f32 v0, v4, v154, v0
	v_fma_f32 v1, v5, v155, v1
	s_nop 0
	v_fma_f32 v0, v6, v156, v0
	v_fma_f32 v1, v7, v157, v1
	s_nop 0
	v_fma_f32 v0, v8, v144, v0
	v_fma_f32 v1, v9, v145, v1
	s_nop 0
	v_fma_f32 v0, v10, v146, v0
	v_fma_f32 v1, v11, v147, v1
	s_nop 0
	v_fma_f32 v0, v12, v148, v0
	v_fma_f32 v1, v13, v149, v1
	s_nop 0
	v_fma_f32 v0, v14, v158, v0
	v_fma_f32 v1, v15, v159, v1
	s_nop 0
	v_fma_f32 v0, v16, v160, v0
	v_fma_f32 v1, v17, v161, v1
	s_nop 0
	v_fma_f32 v0, v18, v164, v0
	v_fma_f32 v1, v19, v165, v1
	s_nop 0
	v_fma_f32 v0, v20, v170, v0
	v_fma_f32 v1, v21, v171, v1
	s_nop 0
	v_fma_f32 v0, v22, v174, v0
	v_fma_f32 v1, v23, v175, v1
	s_nop 0
	v_fma_f32 v0, v24, v162, v0
	v_fma_f32 v1, v25, v163, v1
	s_nop 0
	v_fma_f32 v0, v26, v166, v0
	v_fma_f32 v1, v27, v167, v1
	s_nop 0
	v_fma_f32 v0, v28, v172, v0
	v_fma_f32 v1, v29, v173, v1
	s_nop 0
	v_fma_f32 v208, v30, v176, v0
	v_fma_f32 v209, v31, v177, v1
	s_add_u32 s78, s11, s73
	s_addc_u32 s79, s13, 0
	v_lshl_add_u64 v[0:1], s[78:79], 0, v[138:139]
	v_lshl_add_u64 v[2:3], s[78:79], 0, v[142:143]
	global_load_dwordx4 v[32:35], v[0:1], off
	global_load_dwordx2 v[36:37], v[2:3], off offset:1024
	s_add_u32 s78, s11, s49
	s_addc_u32 s79, s13, 0
	v_lshl_add_u64 v[0:1], s[78:79], 0, v[138:139]
	v_lshl_add_u64 v[2:3], s[78:79], 0, v[142:143]
	global_load_dwordx4 v[38:41], v[0:1], off
	global_load_dwordx2 v[42:43], v[2:3], off offset:1024
	s_add_u32 s78, s11, s71
	s_addc_u32 s79, s13, 0
	v_lshl_add_u64 v[0:1], s[78:79], 0, v[138:139]
	v_lshl_add_u64 v[2:3], s[78:79], 0, v[142:143]
	global_load_dwordx4 v[98:101], v[0:1], off
	global_load_dwordx2 v[102:103], v[2:3], off offset:1024
	s_add_u32 s78, s11, s77
	s_addc_u32 s79, s13, 0
	v_lshl_add_u64 v[0:1], s[78:79], 0, v[138:139]
	v_lshl_add_u64 v[2:3], s[78:79], 0, v[142:143]
	global_load_dwordx4 v[128:131], v[0:1], off
	global_load_dwordx2 v[132:133], v[2:3], off offset:1024
	s_waitcnt vmcnt(9)
; __device__ __forceinline__ void phase_expert(const Params& p, int layer, int row0) {
;     ...
;     for (int i0 = 0; i0 < 128; i0 += 4) {
;       u32x4 ua[4]; u32x2 ub[4];
;       float gk[4];
;       int ek[4];
; #pragma unroll
;       for (int k = 0; k < 4; ++k) {
;         ek[k] = __builtin_amdgcn_readfirstlane(ex[i0 + k]);
;         gk[k] = gt[i0 + k];
;         const unsigned char* up = UB + (size_t)ek[k] * 1536;
;         ua[k] = *(const u32x4*)(up + lane * 16); ub[k] = *(const u32x2*)(up + 1024 + lane * 8);
;       }
;       float dk[4];
; #pragma unroll
;       for (int k = 0; k < 4; ++k) {
;         const u32x6 pk = {ua[k][0], ua[k][1], ua[k][2], ua[k][3], ub[k][0], ub[k][1]};
;         const f32x32 f = __builtin_amdgcn_cvt_scalef32_pk32_f32_fp6(pk, 1.0f);
;         float d0 = 0.f, d1 = 0.f;
; #pragma unroll
;         for (int j = 0; j < 32; j += 2) { d0 += f[j] * u[j]; d1 += f[j + 1] * u[j + 1]; }
;         dk[k] = d0 + d1;
;         __builtin_amdgcn_sched_barrier(0);
;       }
; #pragma unroll
;       for (int k = 0; k < 4; ++k) {
;         const unsigned char* vp = VB + (size_t)ek[k] * 1536;
;         ua[k] = *(const u32x4*)(vp + lane * 16); ub[k] = *(const u32x2*)(vp + 1024 + lane * 8);
;       }
; #pragma unroll
;       for (int o = 32; o >= 1; o >>= 1) {
; #pragma unroll
;         for (int k = 0; k < 4; ++k) dk[k] += __shfl_xor(dk[k], o);
;       }
; #pragma unroll
;       for (int k = 0; k < 4; ++k) {
;         const float a = dk[k] * (1.f / SC_U);
;         const float w = gk[k] * (0.5f * a * (1.f + my_erf(a * 0.7071067811865476f)));
;         const u32x6 pk = {ua[k][0], ua[k][1], ua[k][2], ua[k][3], ub[k][0], ub[k][1]};
;         const f32x32 f = __builtin_amdgcn_cvt_scalef32_pk32_f32_fp6(pk, 1.0f);
; #pragma unroll
;         for (int j = 0; j < 32; ++j) y[j] += w * f[j];
	v_readfirstlane_b32 s73, v252
	v_readfirstlane_b32 s49, v253
	v_readfirstlane_b32 s71, v254
	v_readfirstlane_b32 s77, v255
	s_mulk_i32 s73, 0x600
	s_mulk_i32 s49, 0x600
	s_mulk_i32 s71, 0x600
	s_mulk_i32 s77, 0x600
	s_add_u32 s78, s2, s73
	s_addc_u32 s79, s3, 0
	v_lshl_add_u64 v[0:1], s[78:79], 0, v[138:139]
	v_lshl_add_u64 v[2:3], s[78:79], 0, v[142:143]
	global_load_dwordx4 v[226:229], v[0:1], off
	global_load_dwordx2 v[230:231], v[2:3], off offset:1024
	s_add_u32 s78, s2, s49
	s_addc_u32 s79, s3, 0
	v_lshl_add_u64 v[0:1], s[78:79], 0, v[138:139]
	v_lshl_add_u64 v[2:3], s[78:79], 0, v[142:143]
	global_load_dwordx4 v[232:235], v[0:1], off
	global_load_dwordx2 v[236:237], v[2:3], off offset:1024
	s_add_u32 s78, s2, s71
	s_addc_u32 s79, s3, 0
	v_lshl_add_u64 v[0:1], s[78:79], 0, v[138:139]
	v_lshl_add_u64 v[2:3], s[78:79], 0, v[142:143]
	global_load_dwordx4 v[240:243], v[0:1], off
	global_load_dwordx2 v[244:245], v[2:3], off offset:1024
	s_add_u32 s78, s2, s77
	s_addc_u32 s79, s3, 0
	v_lshl_add_u64 v[0:1], s[78:79], 0, v[138:139]
	v_lshl_add_u64 v[2:3], s[78:79], 0, v[142:143]
	global_load_dwordx4 v[246:249], v[0:1], off
	global_load_dwordx2 v[250:251], v[2:3], off offset:1024
	s_waitcnt vmcnt(14)
	v_cvt_scalef32_pk32_f32_fp6 v[0:31], v[32:37], 1.0
	v_mov_b32_e32 v32, v59
	v_mov_b32_e32 v33, v57
	v_mov_b32_e32 v59, v56
	v_add_f32_e64 v32, v32, v58
	v_add_f32_e64 v33, v33, v59
	ds_bpermute_b32 v35, v217, v33
	ds_bpermute_b32 v34, v217, v32
	s_waitcnt vmcnt(12)
	v_cvt_scalef32_pk32_f32_fp6 v[64:95], v[38:43], 1.0
	s_waitcnt lgkmcnt(0)
	v_add_f32_e64 v32, v32, v34
	v_add_f32_e64 v33, v33, v35
	ds_bpermute_b32 v35, v218, v33
	ds_bpermute_b32 v34, v218, v32
	s_waitcnt lgkmcnt(0)
	v_add_f32_e64 v32, v32, v34
	v_add_f32_e64 v33, v33, v35
	ds_bpermute_b32 v35, v219, v33
	ds_bpermute_b32 v34, v219, v32
	s_waitcnt lgkmcnt(0)
	v_add_f32_e64 v32, v32, v34
	v_add_f32_e64 v33, v33, v35
	ds_bpermute_b32 v35, v220, v33
	ds_bpermute_b32 v34, v220, v32
	s_waitcnt lgkmcnt(0)
	v_add_f32_e64 v32, v32, v34
	v_add_f32_e64 v33, v33, v35
	ds_bpermute_b32 v35, v221, v33
	ds_bpermute_b32 v34, v221, v32
	s_waitcnt lgkmcnt(0)
	v_add_f32_e64 v32, v32, v34
	v_add_f32_e64 v33, v33, v35
	ds_bpermute_b32 v35, v222, v33
	ds_bpermute_b32 v34, v222, v32
	s_waitcnt lgkmcnt(0)
	v_add_f32_e64 v32, v32, v34
	v_add_f32_e64 v33, v33, v35
	s_nop 0
	v_mul_f32_e64 v32, v32, s10
	v_mul_f32_e64 v33, v33, s10
	s_nop 0
	v_mul_f32_e64 v34, v32, s12
	v_mul_f32_e64 v35, v33, s12
	v_mul_f32_e32 v36, 0.5, v33
	v_fma_f32 v33, |v35|, s53, 1.0
	v_div_scale_f32 v45, s[0:1], v33, v33, 1.0
	v_rcp_f32_e32 v48, v45
	v_div_scale_f32 v46, vcc, 1.0, v33, 1.0
	v_mul_f32_e64 v37, |v35|, -|v35|
	v_fma_f32 v51, -v45, v48, 1.0
	v_fmac_f32_e32 v48, v51, v48
	v_mul_f32_e32 v51, v46, v48
	v_fma_f32 v53, -v45, v51, v46
	v_fmac_f32_e32 v51, v53, v48
	v_fma_f32 v45, -v45, v51, v46
	v_div_fmas_f32 v45, v45, v48, v51
	v_div_fixup_f32 v33, v45, v33, 1.0
	v_fma_f32 v44, |v34|, s53, 1.0
	v_mul_f32_e32 v37, 0x3fb8aa3b, v37
	v_fmamk_f32 v45, v33, 0x3f87dc22, v225
	v_div_scale_f32 v47, s[0:1], v44, v44, 1.0
	v_exp_f32_e32 v37, v37
	v_fmaak_f32 v45, v33, v45, 0x3fb5f0e3
	v_rcp_f32_e32 v49, v47
	v_fmaak_f32 v45, v33, v45, 0xbe91a98e
	v_fmaak_f32 v45, v33, v45, 0x3e827906
	v_mul_f32_e32 v33, v33, v45
	v_fma_f32 v33, -v37, v33, 1.0
	v_cmp_gt_f32_e32 vcc, 0, v35
	v_fma_f32 v52, -v47, v49, 1.0
	v_div_scale_f32 v50, s[0:1], 1.0, v44, 1.0
	v_cndmask_b32_e64 v33, v33, -v33, vcc
	v_fmac_f32_e32 v49, v52, v49
	v_add_f32_e32 v33, 1.0, v33
	v_mul_f32_e32 v52, v50, v49
	v_mul_f32_e32 v33, v36, v33
	v_mul_f32_e32 v134, v134, v33
	v_fma_f32 v33, -v47, v52, v50
	v_fmac_f32_e32 v52, v33, v49
	v_fma_f32 v33, -v47, v52, v50
	s_mov_b64 vcc, s[0:1]
	v_div_fmas_f32 v33, v33, v49, v52
	v_div_fixup_f32 v33, v33, v44, 1.0
	v_mul_f32_e64 v36, |v34|, -|v34|
	v_fmamk_f32 v35, v33, 0x3f87dc22, v225
	v_mul_f32_e32 v36, 0x3fb8aa3b, v36
	v_fmaak_f32 v35, v33, v35, 0x3fb5f0e3
	v_exp_f32_e32 v36, v36
	v_fmaak_f32 v35, v33, v35, 0xbe91a98e
	v_fmaak_f32 v35, v33, v35, 0x3e827906
	v_mul_f32_e32 v33, v33, v35
	v_fma_f32 v33, -v36, v33, 1.0
	v_cmp_gt_f32_e32 vcc, 0, v34
	v_mul_f32_e32 v32, 0.5, v32
	s_nop 0
	v_cndmask_b32_e64 v33, v33, -v33, vcc
	v_add_f32_e32 v33, 1.0, v33
	v_mul_f32_e32 v32, v32, v33
	v_mul_f32_e32 v210, v135, v32
	s_waitcnt vmcnt(10)
	v_cvt_scalef32_pk32_f32_fp6 v[32:63], v[98:103], 1.0
	v_mov_b32_e32 v212, v209
	v_mov_b32_e32 v213, v97
	v_mov_b32_e32 v209, v96
	s_waitcnt vmcnt(8)
	v_cvt_scalef32_pk32_f32_fp6 v[96:127], v[128:133], 1.0
	v_fma_f32 v0, v0, v134, v206
	v_fma_f32 v1, v1, v134, v207
	v_add_f32_e64 v128, v212, v208
	v_add_f32_e64 v129, v213, v209
	v_fma_f32 v0, v64, v210, v0
	v_fma_f32 v1, v65, v210, v1
	ds_bpermute_b32 v65, v217, v129
	ds_bpermute_b32 v64, v217, v128
	v_fma_f32 v2, v2, v134, v204
	v_fma_f32 v3, v3, v134, v205
	v_fma_f32 v4, v4, v134, v202
	v_fma_f32 v5, v5, v134, v203
	v_fma_f32 v2, v66, v210, v2
	v_fma_f32 v3, v67, v210, v3
	v_fma_f32 v6, v6, v134, v200
	v_fma_f32 v7, v7, v134, v201
	s_waitcnt lgkmcnt(0)
	v_add_f32_e64 v64, v128, v64
	v_add_f32_e64 v65, v129, v65
	ds_bpermute_b32 v67, v218, v65
	ds_bpermute_b32 v66, v218, v64
	v_fma_f32 v8, v8, v134, v198
	v_fma_f32 v9, v9, v134, v199
	v_fma_f32 v4, v68, v210, v4
	v_fma_f32 v5, v69, v210, v5
	v_fma_f32 v10, v10, v134, v196
	v_fma_f32 v11, v11, v134, v197
	v_fma_f32 v12, v12, v134, v194
	v_fma_f32 v13, v13, v134, v195
	s_waitcnt lgkmcnt(0)
	v_add_f32_e64 v64, v64, v66
	v_add_f32_e64 v65, v65, v67
	ds_bpermute_b32 v67, v219, v65
	ds_bpermute_b32 v66, v219, v64
	v_fma_f32 v6, v70, v210, v6
	v_fma_f32 v7, v71, v210, v7
	v_fma_f32 v8, v72, v210, v8
	v_fma_f32 v9, v73, v210, v9
	v_fma_f32 v10, v74, v210, v10
	v_fma_f32 v11, v75, v210, v11
	v_fma_f32 v12, v76, v210, v12
	v_fma_f32 v13, v77, v210, v13
	s_waitcnt lgkmcnt(0)
; __device__ __forceinline__ void phase_expert(const Params& p, int layer, int row0) {
;     ...
; #pragma unroll
;       for (int o = 32; o >= 1; o >>= 1) {
; #pragma unroll
;         for (int k = 0; k < 4; ++k) dk[k] += __shfl_xor(dk[k], o);
;       }
; #pragma unroll
;       for (int k = 0; k < 4; ++k) {
;         const float a = dk[k] * (1.f / SC_U);
;         const float w = gk[k] * (0.5f * a * (1.f + my_erf(a * 0.7071067811865476f)));
;         const u32x6 pk = {ua[k][0], ua[k][1], ua[k][2], ua[k][3], ub[k][0], ub[k][1]};
;         const f32x32 f = __builtin_amdgcn_cvt_scalef32_pk32_f32_fp6(pk, 1.0f);
; #pragma unroll
;         for (int j = 0; j < 32; ++j) y[j] += w * f[j];
;         __builtin_amdgcn_sched_barrier(0);
;       }
;     }
	v_add_f32_e64 v64, v64, v66
	v_add_f32_e64 v65, v65, v67
	ds_bpermute_b32 v67, v220, v65
	ds_bpermute_b32 v66, v220, v64
	v_fma_f32 v14, v14, v134, v192
	v_fma_f32 v15, v15, v134, v193
	v_fma_f32 v16, v16, v134, v190
	v_fma_f32 v17, v17, v134, v191
	v_fma_f32 v14, v78, v210, v14
	v_fma_f32 v15, v79, v210, v15
	v_fma_f32 v16, v80, v210, v16
	v_fma_f32 v17, v81, v210, v17
	s_waitcnt lgkmcnt(0)
	v_add_f32_e64 v64, v64, v66
	v_add_f32_e64 v65, v65, v67
	ds_bpermute_b32 v67, v221, v65
	ds_bpermute_b32 v66, v221, v64
	v_fma_f32 v18, v18, v134, v188
	v_fma_f32 v19, v19, v134, v189
	v_fma_f32 v20, v20, v134, v186
	v_fma_f32 v21, v21, v134, v187
	v_fma_f32 v22, v22, v134, v184
	v_fma_f32 v23, v23, v134, v185
	v_fma_f32 v24, v24, v134, v182
	v_fma_f32 v25, v25, v134, v183
	s_waitcnt lgkmcnt(0)
	v_add_f32_e64 v64, v64, v66
	v_add_f32_e64 v65, v65, v67
	ds_bpermute_b32 v67, v222, v65
	ds_bpermute_b32 v66, v222, v64
	v_fma_f32 v26, v26, v134, v180
	v_fma_f32 v27, v27, v134, v181
	v_fma_f32 v28, v28, v134, v178
	v_fma_f32 v29, v29, v134, v179
	v_fma_f32 v30, v30, v134, v168
	v_fma_f32 v31, v31, v134, v169
	v_fma_f32 v18, v82, v210, v18
	v_fma_f32 v19, v83, v210, v19
	s_waitcnt lgkmcnt(0)
	v_add_f32_e64 v64, v64, v66
	v_add_f32_e64 v65, v65, v67
	v_fma_f32 v20, v84, v210, v20
	v_fma_f32 v21, v85, v210, v21
	v_mul_f32_e64 v64, v64, s10
	v_mul_f32_e64 v65, v65, s10
	v_fma_f32 v22, v86, v210, v22
	v_fma_f32 v23, v87, v210, v23
	v_mul_f32_e64 v66, v64, s12
	v_mul_f32_e64 v67, v65, s12
	v_mul_f32_e32 v68, 0.5, v65
	v_mul_f32_e32 v65, 0.5, v64
	v_fma_f32 v64, |v67|, s53, 1.0
	v_fma_f32 v70, |v66|, s53, 1.0
	v_div_scale_f32 v72, s[0:1], v64, v64, 1.0
	v_div_scale_f32 v74, s[0:1], v70, v70, 1.0
	v_rcp_f32_e32 v76, v72
	v_rcp_f32_e32 v77, v74
	v_div_scale_f32 v73, vcc, 1.0, v64, 1.0
	v_fma_f32 v78, -v72, v76, 1.0
	v_fma_f32 v79, -v74, v77, 1.0
	v_fmac_f32_e32 v76, v78, v76
	v_div_scale_f32 v75, s[0:1], 1.0, v70, 1.0
	v_fmac_f32_e32 v77, v79, v77
	v_mul_f32_e32 v78, v73, v76
	v_mul_f32_e32 v79, v75, v77
	v_fma_f32 v80, -v72, v78, v73
	v_fma_f32 v81, -v74, v79, v75
	v_fmac_f32_e32 v78, v80, v76
	v_fmac_f32_e32 v79, v81, v77
	v_fma_f32 v72, -v72, v78, v73
	v_fma_f32 v73, -v74, v79, v75
	v_div_fmas_f32 v72, v72, v76, v78
	s_mov_b64 vcc, s[0:1]
	v_mul_f32_e64 v69, |v67|, -|v67|
	v_div_fixup_f32 v64, v72, v64, 1.0
	v_div_fmas_f32 v72, v73, v77, v79
	v_mul_f32_e64 v71, |v66|, -|v66|
	v_mul_f32_e32 v69, 0x3fb8aa3b, v69
	v_fmamk_f32 v73, v64, 0x3f87dc22, v225
	v_div_fixup_f32 v70, v72, v70, 1.0
	v_mul_f32_e32 v71, 0x3fb8aa3b, v71
	v_exp_f32_e32 v69, v69
	v_fmaak_f32 v72, v64, v73, 0x3fb5f0e3
	v_fmamk_f32 v73, v70, 0x3f87dc22, v225
	v_exp_f32_e32 v71, v71
	v_fmaak_f32 v72, v64, v72, 0xbe91a98e
	v_fmaak_f32 v73, v70, v73, 0x3fb5f0e3
	v_fmaak_f32 v72, v64, v72, 0x3e827906
	v_fmaak_f32 v73, v70, v73, 0xbe91a98e
	v_mul_f32_e32 v64, v64, v72
	v_fmaak_f32 v72, v70, v73, 0x3e827906
	v_fma_f32 v64, -v69, v64, 1.0
	v_cmp_gt_f32_e32 vcc, 0, v67
	v_mul_f32_e32 v67, v70, v72
	v_fma_f32 v67, -v71, v67, 1.0
	v_cmp_gt_f32_e64 s[0:1], 0, v66
	v_cndmask_b32_e64 v64, v64, -v64, vcc
	v_add_f32_e32 v64, 1.0, v64
	v_cndmask_b32_e64 v66, v67, -v67, s[0:1]
	v_mul_f32_e32 v64, v68, v64
	v_add_f32_e32 v66, 1.0, v66
	v_fma_f32 v24, v88, v210, v24
	v_fma_f32 v25, v89, v210, v25
	v_fma_f32 v26, v90, v210, v26
	v_fma_f32 v27, v91, v210, v27
	v_fma_f32 v28, v92, v210, v28
	v_fma_f32 v29, v93, v210, v29
	v_fma_f32 v30, v94, v210, v30
	v_fma_f32 v31, v95, v210, v31
	v_mul_f32_e32 v64, v136, v64
	v_mul_f32_e32 v65, v65, v66
	v_mul_f32_e32 v66, v137, v65
	v_fma_f32 v0, v32, v64, v0
	v_fma_f32 v1, v33, v64, v1
	v_fma_f32 v2, v34, v64, v2
	v_fma_f32 v3, v35, v64, v3
	v_fma_f32 v4, v36, v64, v4
	v_fma_f32 v5, v37, v64, v5
	v_fma_f32 v6, v38, v64, v6
	v_fma_f32 v7, v39, v64, v7
	v_fma_f32 v8, v40, v64, v8
	v_fma_f32 v9, v41, v64, v9
	v_fma_f32 v10, v42, v64, v10
	v_fma_f32 v11, v43, v64, v11
	v_fma_f32 v12, v44, v64, v12
	v_fma_f32 v13, v45, v64, v13
	v_fma_f32 v14, v46, v64, v14
	v_fma_f32 v15, v47, v64, v15
	v_fma_f32 v16, v48, v64, v16
	v_fma_f32 v17, v49, v64, v17
	v_fma_f32 v18, v50, v64, v18
	v_fma_f32 v19, v51, v64, v19
	v_fma_f32 v20, v52, v64, v20
	v_fma_f32 v21, v53, v64, v21
	v_fma_f32 v22, v54, v64, v22
	v_fma_f32 v23, v55, v64, v23
	v_fma_f32 v24, v56, v64, v24
	v_fma_f32 v25, v57, v64, v25
	v_fma_f32 v26, v58, v64, v26
	v_fma_f32 v27, v59, v64, v27
	v_fma_f32 v28, v60, v64, v28
	v_fma_f32 v29, v61, v64, v29
	v_fma_f32 v30, v62, v64, v30
	v_fma_f32 v31, v63, v64, v31
	v_fma_f32 v206, v96, v66, v0
	v_fma_f32 v207, v97, v66, v1
	v_fma_f32 v204, v98, v66, v2
	v_fma_f32 v205, v99, v66, v3
	v_fma_f32 v202, v100, v66, v4
	v_fma_f32 v203, v101, v66, v5
	v_fma_f32 v200, v102, v66, v6
	v_fma_f32 v201, v103, v66, v7
	v_fma_f32 v198, v104, v66, v8
	v_fma_f32 v199, v105, v66, v9
	v_fma_f32 v196, v106, v66, v10
	v_fma_f32 v197, v107, v66, v11
	v_fma_f32 v194, v108, v66, v12
	v_fma_f32 v195, v109, v66, v13
	v_fma_f32 v192, v110, v66, v14
	v_fma_f32 v193, v111, v66, v15
	v_fma_f32 v190, v112, v66, v16
	v_fma_f32 v191, v113, v66, v17
	v_fma_f32 v188, v114, v66, v18
	v_fma_f32 v189, v115, v66, v19
	v_fma_f32 v186, v116, v66, v20
	v_fma_f32 v187, v117, v66, v21
	v_fma_f32 v184, v118, v66, v22
	v_fma_f32 v185, v119, v66, v23
	v_fma_f32 v182, v120, v66, v24
	v_fma_f32 v183, v121, v66, v25
	v_fma_f32 v180, v122, v66, v26
	v_fma_f32 v181, v123, v66, v27
	v_fma_f32 v178, v124, v66, v28
	v_fma_f32 v179, v125, v66, v29
	v_fma_f32 v168, v126, v66, v30
	v_fma_f32 v169, v127, v66, v31
	s_add_i32 s69, s69, 4
	s_add_u32 s50, s50, 16
	s_addc_u32 s51, s51, 0
	s_cmpk_gt_u32 s69, 0x7b
	s_cbranch_scc0 .LBB0_1933
; DI const float* modp(const Params& p, int layer, int v) { return (const float*)(p.ws + OFF_MOD) + (size_t)(layer * 2 + v) * 12288; }
; __device__ __forceinline__ void phase_expert(const Params& p, int layer, int row0) {
;     ...
;     int lane2 = lane; asm volatile("" : "+v"(lane2));
;     const int v = row < NCTX ? 1 : 0;
;     const float* md = modp(p, layer, v);
;     float pre[32];
;     float s = 0.f;
; #pragma unroll
;     for (int c = 0; c < 2; ++c) {
; #pragma unroll
;       for (int q4 = 0; q4 < 4; ++q4) {
;         const int col = c * 1024 + lane2 * 16 + q4 * 4;
;         const f32x4 a = *(const f32x4*)(XR + (size_t)row * LDF + col);
;         const f32x4 g2 = *(const f32x4*)(md + 10240 + col);
; #pragma unroll
;         for (int e = 0; e < 4; ++e) {
;           const float pv = ALPHA * a[e] + g2[e] * (y[c * 16 + q4 * 4 + e] * (1.f / SC_V));
;           pre[c * 16 + q4 * 4 + e] = pv; s += pv;
;         }
;       }
;     }
;     const float mu = wave_sum(s) * (1.f / 2048.f);
	v_mov_b32_e32 v0, v216
	s_cmpk_lt_i32 s48, 0x100
	s_cselect_b32 s1, 0xc000, 0
	v_lshlrev_b32_e32 v0, 4, v0
	s_cselect_b32 s0, s60, 0x18000
	s_add_u32 s50, s46, s1
	v_ashrrev_i32_e32 v1, 31, v0
	s_addc_u32 s51, s47, 0
	v_lshlrev_b64 v[8:9], 2, v[0:1]
	v_lshl_add_u64 v[2:3], s[50:51], 0, v[8:9]
	s_mul_hi_i32 s1, s48, 0x2080
	s_mulk_i32 s48, 0x2080
	v_lshl_add_u64 v[4:5], v[2:3], 0, s[14:15]
	v_lshl_add_u64 v[58:59], v[2:3], 0, s[20:21]
	v_add_co_u32_e32 v2, vcc, s62, v2
	s_add_u32 s48, s34, s48
	s_nop 0
	v_addc_co_u32_e32 v3, vcc, 0, v3, vcc
	s_addc_u32 s49, s35, s1
	global_load_dwordx4 v[10:13], v[4:5], off offset:32
	global_load_dwordx4 v[14:17], v[4:5], off offset:16
	global_load_dwordx4 v[18:21], v[58:59], off offset:32
	global_load_dwordx4 v[22:25], v[58:59], off offset:48
	global_load_dwordx4 v[26:29], v[2:3], off offset:-4096
	global_load_dwordx4 v[34:37], v[2:3], off
	global_load_dwordx4 v[30:33], v[4:5], off offset:48
	v_lshl_add_u64 v[4:5], s[48:49], 0, v[8:9]
	v_lshl_add_u64 v[6:7], v[4:5], 0, s[18:19]
	v_add_co_u32_e32 v2, vcc, s61, v4
	global_load_dwordx4 v[38:41], v[6:7], off offset:48
	global_load_dwordx4 v[42:45], v[4:5], off offset:16
	global_load_dwordx4 v[46:49], v[4:5], off
	global_load_dwordx4 v[50:53], v[4:5], off offset:32
	global_load_dwordx4 v[54:57], v[4:5], off offset:48
	s_nop 0
	global_load_dwordx4 v[58:61], v[58:59], off offset:16
	v_addc_co_u32_e32 v3, vcc, 0, v5, vcc
	global_load_dwordx4 v[62:65], v[2:3], off
	global_load_dwordx4 v[66:69], v[6:7], off offset:32
	global_load_dwordx4 v[70:73], v[6:7], off offset:16
	v_mul_f32_e64 v74, v206, s16
	v_mul_f32_e64 v75, v207, s16
	v_mul_f32_e64 v102, v178, s16
	v_mul_f32_e64 v103, v179, s16
	v_mul_f32_e64 v76, v204, s16
	v_mul_f32_e64 v77, v205, s16
	v_mul_f32_e64 v78, v202, s16
	v_mul_f32_e64 v79, v203, s16
	v_mul_f32_e64 v104, v168, s16
	v_mul_f32_e64 v105, v169, s16
	v_mul_f32_e64 v84, v196, s16
	v_mul_f32_e64 v85, v197, s16
	v_mul_f32_e64 v94, v186, s16
	v_mul_f32_e64 v95, v187, s16
	v_mul_f32_e64 v80, v200, s16
	v_mul_f32_e64 v81, v201, s16
	v_mul_f32_e64 v82, v198, s16
	v_mul_f32_e64 v83, v199, s16
	v_mul_f32_e64 v86, v194, s16
	v_mul_f32_e64 v87, v195, s16
	v_mul_f32_e64 v88, v192, s16
	v_mul_f32_e64 v89, v193, s16
	v_mul_f32_e64 v90, v190, s16
	v_mul_f32_e64 v91, v191, s16
	v_mul_f32_e64 v92, v188, s16
	v_mul_f32_e64 v93, v189, s16
	v_mul_f32_e64 v96, v184, s16
	v_mul_f32_e64 v97, v185, s16
	v_mul_f32_e64 v98, v182, s16
	v_mul_f32_e64 v99, v183, s16
	v_mul_f32_e64 v100, v180, s16
	v_mul_f32_e64 v101, v181, s16
	s_add_u32 s0, s46, s0
	s_addc_u32 s1, s47, 0
	s_add_u32 s48, s8, s68
	s_addc_u32 s49, s9, s67
	v_add_u32_e32 v215, s52, v215
	s_waitcnt vmcnt(15)
	v_mul_f32_e64 v12, v84, v12
	v_mul_f32_e64 v13, v85, v13
	s_waitcnt vmcnt(14)
	v_mul_f32_e64 v14, v78, v14
	v_mul_f32_e64 v15, v79, v15
	s_waitcnt vmcnt(12)
	v_mul_f32_e64 v22, v102, v22
	v_mul_f32_e64 v23, v103, v23
	s_waitcnt vmcnt(11)
	v_mul_f32_e64 v26, v74, v26
	v_mul_f32_e64 v27, v75, v27
	v_mul_f32_e64 v24, v104, v24
	v_mul_f32_e64 v25, v105, v25
	v_mul_f32_e64 v28, v76, v28
	v_mul_f32_e64 v29, v77, v29
	s_waitcnt vmcnt(8)
	v_fma_f32 v74, v38, s24, v22
	v_fma_f32 v75, v39, s24, v23
	s_waitcnt vmcnt(6)
	v_fma_f32 v22, v46, s24, v26
	v_fma_f32 v23, v47, s24, v27
	v_fma_f32 v40, v40, s24, v24
	v_fma_f32 v41, v41, s24, v25
	v_fma_f32 v14, v42, s24, v14
	v_fma_f32 v15, v43, s24, v15
	v_fma_f32 v42, v48, s24, v28
	v_fma_f32 v43, v49, s24, v29
	s_waitcnt vmcnt(3)
	v_mul_f32_e64 v24, v94, v58
	v_mul_f32_e64 v25, v95, v59
	v_add_f32_e32 v28, 0, v22
	v_fma_f32 v12, v52, s24, v12
	v_fma_f32 v13, v53, s24, v13
	s_waitcnt vmcnt(0)
	v_fma_f32 v52, v70, s24, v24
	v_fma_f32 v53, v71, s24, v25
	v_add_f32_e32 v24, v23, v28
	v_add_f32_e32 v24, v42, v24
	v_add_f32_e32 v24, v43, v24
	v_mul_f32_e64 v16, v80, v16
	v_mul_f32_e64 v17, v81, v17
	v_add_f32_e32 v24, v14, v24
	v_fma_f32 v16, v44, s24, v16
	v_fma_f32 v17, v45, s24, v17
	v_add_f32_e32 v24, v15, v24
	v_mul_f32_e64 v10, v82, v10
	v_mul_f32_e64 v11, v83, v11
	v_add_f32_e32 v24, v16, v24
	v_fma_f32 v10, v50, s24, v10
	v_fma_f32 v11, v51, s24, v11
	v_add_f32_e32 v24, v17, v24
	v_add_f32_e32 v24, v10, v24
	v_add_f32_e32 v24, v11, v24
	v_mul_f32_e64 v30, v86, v30
	v_mul_f32_e64 v31, v87, v31
	v_add_f32_e32 v24, v12, v24
	v_fma_f32 v44, v54, s24, v30
	v_fma_f32 v45, v55, s24, v31
	v_add_f32_e32 v24, v13, v24
	v_mul_f32_e64 v32, v88, v32
	v_mul_f32_e64 v33, v89, v33
	v_add_f32_e32 v24, v44, v24
	v_fma_f32 v46, v56, s24, v32
	v_fma_f32 v47, v57, s24, v33
	v_add_f32_e32 v24, v45, v24
	v_mul_f32_e64 v34, v90, v34
	v_mul_f32_e64 v35, v91, v35
	v_add_f32_e32 v24, v46, v24
	v_fma_f32 v48, v62, s24, v34
	v_fma_f32 v49, v63, s24, v35
	v_add_f32_e32 v24, v47, v24
	v_mul_f32_e64 v36, v92, v36
	v_mul_f32_e64 v37, v93, v37
	v_add_f32_e32 v24, v48, v24
	v_fma_f32 v50, v64, s24, v36
	v_fma_f32 v51, v65, s24, v37
	v_add_f32_e32 v24, v49, v24
	v_add_f32_e32 v24, v50, v24
	v_add_f32_e32 v24, v51, v24
	v_mul_f32_e64 v26, v96, v60
	v_mul_f32_e64 v27, v97, v61
	v_add_f32_e32 v24, v52, v24
	v_fma_f32 v54, v72, s24, v26
	v_fma_f32 v55, v73, s24, v27
	v_add_f32_e32 v24, v53, v24
	v_mul_f32_e64 v18, v98, v18
	v_mul_f32_e64 v19, v99, v19
	v_add_f32_e32 v24, v54, v24
	v_fma_f32 v18, v66, s24, v18
	v_fma_f32 v19, v67, s24, v19
	v_add_f32_e32 v24, v55, v24
	v_add_f32_e32 v24, v18, v24
	v_mul_f32_e64 v20, v100, v20
	v_mul_f32_e64 v21, v101, v21
	v_add_f32_e32 v24, v19, v24
	v_fma_f32 v20, v68, s24, v20
	v_fma_f32 v21, v69, s24, v21
	v_lshl_add_u64 v[56:57], s[42:43], 0, v[8:9]
	v_add_f32_e32 v24, v20, v24
	v_add_f32_e32 v24, v21, v24
	v_add_f32_e32 v24, v74, v24
	v_add_f32_e32 v24, v75, v24
	v_add_f32_e32 v24, v40, v24
	v_add_f32_e32 v24, v41, v24
	ds_bpermute_b32 v25, v217, v24
	v_lshl_add_u64 v[58:59], s[44:45], 0, v[8:9]
	v_lshl_add_u64 v[8:9], s[0:1], 0, v[8:9]
	s_waitcnt lgkmcnt(0)
; DI unsigned pk2(float a, float b) { f32x2 v = {a, b}; bf2_t r = __builtin_convertvector(v, bf2_t); return __builtin_bit_cast(unsigned, r); }
; DI const float* modp(const Params& p, int layer, int v) { return (const float*)(p.ws + OFF_MOD) + (size_t)(layer * 2 + v) * 12288; }
; __device__ __forceinline__ void phase_expert(const Params& p, int layer, int row0) {
;     ...
;     const float mu = wave_sum(s) * (1.f / 2048.f);
;     float q = 0.f;
; #pragma unroll
;     for (int e = 0; e < 32; ++e) { float d = pre[e] - mu; q += d * d; }
;     const float rstd = rsqrtf(wave_sum(q) * (1.f / 2048.f) + LN_EPS);
;     const float* mdn = modp(p, 1, v);
; #pragma unroll
;     for (int c = 0; c < 2; ++c) {
; #pragma unroll
;       for (int q8 = 0; q8 < 2; ++q8) {
;         const int col = c * 1024 + lane2 * 16 + q8 * 8;
;         float o[8];
; #pragma unroll
;         for (int e = 0; e < 8; ++e) o[e] = (pre[c * 16 + q8 * 8 + e] - mu) * rstd * G[col + e] + B[col + e];
;         if (layer == 0) {
;           *(f32x4*)(XR + (size_t)row * LDF + col) = f32x4{o[0], o[1], o[2], o[3]};
;           *(f32x4*)(XR + (size_t)row * LDF + col + 4) = f32x4{o[4], o[5], o[6], o[7]};
;           float z[8];
; #pragma unroll
;           for (int e = 0; e < 8; ++e) z[e] = o[e] * (1.f + mdn[2048 + col + e]) + mdn[col + e];
;           *(u32x4*)(XMo + (size_t)row * LDX + col) = u32x4{pk2(z[0], z[1]), pk2(z[2], z[3]), pk2(z[4], z[5]), pk2(z[6], z[7])};
	v_add_f32_e32 v24, v24, v25
	ds_bpermute_b32 v25, v218, v24
	s_waitcnt lgkmcnt(0)
	v_add_f32_e32 v24, v24, v25
	ds_bpermute_b32 v25, v219, v24
	s_waitcnt lgkmcnt(0)
	v_add_f32_e32 v24, v24, v25
	ds_bpermute_b32 v25, v220, v24
	s_waitcnt lgkmcnt(0)
	v_add_f32_e32 v24, v24, v25
	ds_bpermute_b32 v25, v221, v24
	s_waitcnt lgkmcnt(0)
	v_add_f32_e32 v60, v24, v25
	ds_bpermute_b32 v61, v222, v60
	global_load_dwordx4 v[24:27], v[56:57], off offset:16
	global_load_dwordx4 v[28:31], v[56:57], off
	global_load_dwordx4 v[32:35], v[58:59], off offset:16
	global_load_dwordx4 v[36:39], v[58:59], off
	s_waitcnt lgkmcnt(0)
	v_add_f32_e32 v60, v60, v61
	v_mul_f32_e32 v60, 0x3a000000, v60
	v_add_f32_e64 v62, v22, -v60
	v_add_f32_e64 v63, v23, -v60
	v_add_f32_e64 v42, v42, -v60
	v_add_f32_e64 v43, v43, -v60
	v_add_f32_e64 v72, v44, -v60
	v_add_f32_e64 v73, v45, -v60
	v_mul_f32_e64 v44, v62, v62
	v_mul_f32_e64 v45, v63, v63
	v_add_f32_e64 v76, v46, -v60
	v_add_f32_e64 v77, v47, -v60
	v_mul_f32_e64 v46, v42, v42
	v_mul_f32_e64 v47, v43, v43
	v_add_f32_e32 v44, v44, v45
	v_add_f32_e64 v64, v14, -v60
	v_add_f32_e64 v65, v15, -v60
	v_add_f32_e32 v44, v46, v44
	v_add_f32_e64 v22, v48, -v60
	v_add_f32_e64 v23, v49, -v60
	v_mul_f32_e64 v48, v64, v64
	v_mul_f32_e64 v49, v65, v65
	v_add_f32_e32 v44, v47, v44
	v_add_f32_e64 v66, v16, -v60
	v_add_f32_e64 v67, v17, -v60
	v_add_f32_e32 v44, v48, v44
	v_mul_f32_e64 v78, v66, v66
	v_mul_f32_e64 v79, v67, v67
	v_add_f32_e32 v44, v49, v44
	v_add_f32_e64 v68, v10, -v60
	v_add_f32_e64 v69, v11, -v60
	v_add_f32_e32 v44, v78, v44
	v_mul_f32_e64 v80, v68, v68
	v_mul_f32_e64 v81, v69, v69
	v_add_f32_e32 v44, v79, v44
	v_add_f32_e64 v70, v12, -v60
	v_add_f32_e64 v71, v13, -v60
	v_add_f32_e32 v44, v80, v44
	v_mul_f32_e64 v82, v70, v70
	v_mul_f32_e64 v83, v71, v71
	v_add_f32_e32 v44, v81, v44
	v_add_f32_e32 v44, v82, v44
	v_mul_f32_e64 v84, v72, v72
	v_mul_f32_e64 v85, v73, v73
	v_add_f32_e32 v44, v83, v44
	v_add_f32_e32 v44, v84, v44
	v_mul_f32_e64 v86, v76, v76
	v_mul_f32_e64 v87, v77, v77
	v_add_f32_e32 v44, v85, v44
	v_add_f32_e32 v44, v86, v44
	v_mul_f32_e64 v88, v22, v22
	v_mul_f32_e64 v89, v23, v23
	v_add_f32_e32 v44, v87, v44
	v_add_f32_e64 v90, v50, -v60
	v_add_f32_e64 v91, v51, -v60
	v_add_f32_e32 v44, v88, v44
	v_mul_f32_e64 v50, v90, v90
	v_mul_f32_e64 v51, v91, v91
	v_add_f32_e32 v44, v89, v44
	v_add_f32_e64 v52, v52, -v60
	v_add_f32_e64 v53, v53, -v60
	v_add_f32_e32 v44, v50, v44
	v_mul_f32_e64 v92, v52, v52
	v_mul_f32_e64 v93, v53, v53
	v_add_f32_e32 v44, v51, v44
	v_add_f32_e64 v54, v54, -v60
	v_add_f32_e64 v55, v55, -v60
	v_add_f32_e32 v44, v92, v44
	v_mul_f32_e64 v94, v54, v54
	v_mul_f32_e64 v95, v55, v55
	v_add_f32_e32 v44, v93, v44
	v_add_f32_e64 v14, v18, -v60
	v_add_f32_e64 v15, v19, -v60
	v_add_f32_e32 v44, v94, v44
	v_mul_f32_e64 v18, v14, v14
	v_mul_f32_e64 v19, v15, v15
	v_add_f32_e32 v44, v95, v44
	v_add_f32_e64 v16, v20, -v60
	v_add_f32_e64 v17, v21, -v60
	v_add_f32_e32 v18, v18, v44
	v_mul_f32_e64 v20, v16, v16
	v_mul_f32_e64 v21, v17, v17
	v_add_f32_e32 v18, v19, v18
	v_add_f32_e64 v10, v74, -v60
	v_add_f32_e64 v11, v75, -v60
	v_add_f32_e32 v18, v20, v18
	v_mul_f32_e64 v74, v10, v10
	v_mul_f32_e64 v75, v11, v11
	v_add_f32_e32 v18, v21, v18
	v_add_f32_e64 v12, v40, -v60
	v_add_f32_e64 v13, v41, -v60
	v_add_f32_e32 v18, v74, v18
	v_mul_f32_e64 v40, v12, v12
	v_mul_f32_e64 v41, v13, v13
	v_add_f32_e32 v18, v75, v18
	v_add_f32_e32 v18, v40, v18
	v_add_f32_e32 v18, v41, v18
	ds_bpermute_b32 v19, v217, v18
	s_waitcnt lgkmcnt(0)
	v_add_f32_e32 v18, v18, v19
	ds_bpermute_b32 v19, v218, v18
	s_waitcnt lgkmcnt(0)
	v_add_f32_e32 v18, v18, v19
	ds_bpermute_b32 v19, v219, v18
	s_waitcnt lgkmcnt(0)
	v_add_f32_e32 v18, v18, v19
	ds_bpermute_b32 v19, v220, v18
	s_waitcnt lgkmcnt(0)
	v_add_f32_e32 v18, v18, v19
	ds_bpermute_b32 v19, v221, v18
	s_waitcnt lgkmcnt(0)
	v_add_f32_e32 v18, v18, v19
	ds_bpermute_b32 v19, v222, v18
	s_waitcnt lgkmcnt(0)
	v_add_f32_e32 v18, v18, v19
	v_mov_b32_e32 v226, 0x3727c5ac
	v_fmamk_f32 v18, v18, 0x3a000000, v226
	v_mul_f32_e32 v19, 0x4b800000, v18
	v_cmp_gt_f32_e32 vcc, s63, v18
	s_nop 1
	v_cndmask_b32_e32 v18, v18, v19, vcc
	v_rsq_f32_e32 v18, v18
	s_nop 0
	v_mul_f32_e32 v19, 0x45800000, v18
	v_cndmask_b32_e32 v20, v18, v19, vcc
	v_mul_f32_e64 v18, v62, v20
	v_mul_f32_e64 v19, v63, v20
	v_mul_f32_e64 v40, v42, v20
	v_mul_f32_e64 v41, v43, v20
	v_mul_f32_e64 v42, v64, v20
	v_mul_f32_e64 v43, v65, v20
	v_mul_f32_e64 v44, v66, v20
	v_mul_f32_e64 v45, v67, v20
	s_waitcnt vmcnt(0)
	v_fma_f32 v28, v28, v18, v36
	v_fma_f32 v29, v29, v19, v37
	v_fma_f32 v30, v30, v40, v38
	v_fma_f32 v31, v31, v41, v39
	v_fma_f32 v32, v24, v42, v32
	v_fma_f32 v33, v25, v43, v33
	v_add_co_u32_e32 v24, vcc, s65, v8
	v_fma_f32 v34, v26, v44, v34
	v_fma_f32 v35, v27, v45, v35
	global_store_dwordx4 v[4:5], v[28:31], off
	global_store_dwordx4 v[4:5], v[32:35], off offset:16
	v_addc_co_u32_e32 v25, vcc, 0, v9, vcc
	global_load_dwordx4 v[36:39], v[24:25], off offset:-4096
	v_lshl_add_u64 v[18:19], v[8:9], 0, s[26:27]
	global_load_dwordx4 v[40:43], v[18:19], off offset:16
	global_load_dwordx4 v[44:47], v[8:9], off
	global_load_dwordx4 v[48:51], v[8:9], off offset:16
	v_lshl_add_u64 v[18:19], v[0:1], 1, s[48:49]
	v_mul_f32_e64 v22, v22, v20
	v_mul_f32_e64 v23, v23, v20
	v_mul_f32_e64 v10, v10, v20
	v_mul_f32_e64 v11, v11, v20
	v_mul_f32_e64 v12, v12, v20
	v_mul_f32_e64 v13, v13, v20
	s_waitcnt vmcnt(3)
	v_add_f32_e64 v26, v36, 1.0
	v_add_f32_e64 v27, v37, 1.0
	v_add_f32_e64 v36, v38, 1.0
	v_add_f32_e64 v37, v39, 1.0
	s_waitcnt vmcnt(2)
	v_add_f32_e64 v38, v40, 1.0
	v_add_f32_e64 v39, v41, 1.0
	v_add_f32_e64 v40, v42, 1.0
	v_add_f32_e64 v41, v43, 1.0
	s_waitcnt vmcnt(1)
; DI unsigned pk2(float a, float b) { f32x2 v = {a, b}; bf2_t r = __builtin_convertvector(v, bf2_t); return __builtin_bit_cast(unsigned, r); }
; __device__ __forceinline__ void phase_expert(const Params& p, int layer, int row0) {
;     ...
; #pragma unroll
;     for (int c = 0; c < 2; ++c) {
; #pragma unroll
;       for (int q8 = 0; q8 < 2; ++q8) {
;         const int col = c * 1024 + lane2 * 16 + q8 * 8;
;         float o[8];
; #pragma unroll
;         for (int e = 0; e < 8; ++e) o[e] = (pre[c * 16 + q8 * 8 + e] - mu) * rstd * G[col + e] + B[col + e];
;         if (layer == 0) {
;           *(f32x4*)(XR + (size_t)row * LDF + col) = f32x4{o[0], o[1], o[2], o[3]};
;           *(f32x4*)(XR + (size_t)row * LDF + col + 4) = f32x4{o[4], o[5], o[6], o[7]};
;           float z[8];
; #pragma unroll
;           for (int e = 0; e < 8; ++e) z[e] = o[e] * (1.f + mdn[2048 + col + e]) + mdn[col + e];
;           *(u32x4*)(XMo + (size_t)row * LDX + col) = u32x4{pk2(z[0], z[1]), pk2(z[2], z[3]), pk2(z[4], z[5]), pk2(z[6], z[7])};
	v_fma_f32 v26, v26, v28, v44
	v_fma_f32 v27, v27, v29, v45
	v_fma_f32 v28, v36, v30, v46
	v_fma_f32 v29, v37, v31, v47
	s_waitcnt vmcnt(0)
	v_fma_f32 v30, v38, v32, v48
	v_fma_f32 v31, v39, v33, v49
	v_fma_f32 v32, v40, v34, v50
	v_fma_f32 v33, v41, v35, v51
	v_cvt_pk_bf16_f32 v26, v26, v27
	v_cvt_pk_bf16_f32 v27, v28, v29
	v_cvt_pk_bf16_f32 v28, v30, v31
	v_cvt_pk_bf16_f32 v29, v32, v33
	global_store_dwordx4 v[18:19], v[26:29], off
	global_load_dwordx4 v[26:29], v[58:59], off offset:32
	s_nop 0
	global_load_dwordx4 v[30:33], v[56:57], off offset:32
	global_load_dwordx4 v[34:37], v[56:57], off offset:48
	global_load_dwordx4 v[38:41], v[58:59], off offset:48
	v_mul_f32_e64 v44, v68, v20
	v_mul_f32_e64 v45, v69, v20
	v_mul_f32_e64 v46, v70, v20
	v_mul_f32_e64 v47, v71, v20
	v_add_co_u32_e32 v42, vcc, s64, v8
	v_mul_f32_e64 v48, v72, v20
	v_mul_f32_e64 v49, v73, v20
	v_mul_f32_e64 v50, v76, v20
	v_mul_f32_e64 v51, v77, v20
	v_addc_co_u32_e32 v43, vcc, 0, v9, vcc
	v_add_co_u32_e32 v56, vcc, s61, v56
	s_waitcnt vmcnt(2)
	v_fma_f32 v26, v30, v44, v26
	v_fma_f32 v27, v31, v45, v27
	v_fma_f32 v28, v32, v46, v28
	v_fma_f32 v29, v33, v47, v29
	s_waitcnt vmcnt(0)
	v_fma_f32 v30, v34, v48, v38
	v_fma_f32 v31, v35, v49, v39
	v_fma_f32 v32, v36, v50, v40
	v_fma_f32 v33, v37, v51, v41
	global_store_dwordx4 v[4:5], v[26:29], off offset:32
	global_store_dwordx4 v[4:5], v[30:33], off offset:48
	global_load_dwordx4 v[34:37], v[42:43], off offset:32
	v_lshl_add_u64 v[38:39], v[8:9], 0, s[28:29]
	global_load_dwordx4 v[38:41], v[38:39], off offset:16
	s_nop 0
	global_load_dwordx4 v[42:45], v[8:9], off offset:32
	global_load_dwordx4 v[46:49], v[8:9], off offset:48
	v_add_u32_e32 v50, 0x402, v0
	v_ashrrev_i32_e32 v51, 31, v50
	v_addc_co_u32_e32 v57, vcc, 0, v57, vcc
	v_lshlrev_b64 v[50:51], 2, v[50:51]
	v_add_co_u32_e32 v58, vcc, s61, v58
	v_lshl_add_u64 v[60:61], s[42:43], 0, v[50:51]
	v_lshl_add_u64 v[62:63], s[44:45], 0, v[50:51]
	v_addc_co_u32_e32 v59, vcc, 0, v59, vcc
	v_add_u32_e32 v0, 0x40a, v0
	v_ashrrev_i32_e32 v1, 31, v0
	s_waitcnt vmcnt(3)
	v_add_f32_e64 v34, v34, 1.0
	v_add_f32_e64 v35, v35, 1.0
	v_add_f32_e64 v36, v36, 1.0
	v_add_f32_e64 v37, v37, 1.0
	s_waitcnt vmcnt(2)
	v_add_f32_e64 v38, v38, 1.0
	v_add_f32_e64 v39, v39, 1.0
	v_add_f32_e64 v40, v40, 1.0
	v_add_f32_e64 v41, v41, 1.0
	s_waitcnt vmcnt(1)
	v_fma_f32 v26, v34, v26, v42
	v_fma_f32 v27, v35, v27, v43
	v_fma_f32 v28, v36, v28, v44
	v_fma_f32 v29, v37, v29, v45
	s_waitcnt vmcnt(0)
	v_fma_f32 v30, v38, v30, v46
	v_fma_f32 v31, v39, v31, v47
	v_fma_f32 v32, v32, v40, v48
	v_fma_f32 v33, v33, v41, v49
	v_cvt_pk_bf16_f32 v26, v26, v27
	v_cvt_pk_bf16_f32 v27, v28, v29
	v_cvt_pk_bf16_f32 v28, v30, v31
	v_cvt_pk_bf16_f32 v29, v32, v33
	global_store_dwordx4 v[18:19], v[26:29], off offset:16
	global_load_dwordx2 v[34:35], v[56:57], off
	global_load_dwordx2 v[36:37], v[58:59], off
	s_nop 0
	global_load_dwordx4 v[26:29], v[62:63], off
	global_load_dwordx4 v[30:33], v[60:61], off
	global_load_dwordx2 v[38:39], v[60:61], off offset:16
	global_load_dwordx2 v[40:41], v[62:63], off offset:16
	v_mul_f32_e64 v44, v90, v20
	v_mul_f32_e64 v45, v91, v20
	v_lshl_add_u64 v[46:47], s[0:1], 0, v[50:51]
	v_mul_f32_e64 v48, v52, v20
	v_mul_f32_e64 v49, v53, v20
	v_mul_f32_e64 v50, v54, v20
	v_mul_f32_e64 v51, v55, v20
	v_lshl_add_u64 v[42:43], v[8:9], 0, s[30:31]
	s_waitcnt vmcnt(4)
	v_fma_f32 v34, v22, v34, v36
	v_fma_f32 v35, v23, v35, v37
	v_add_co_u32_e32 v22, vcc, s61, v8
	s_waitcnt vmcnt(2)
; DI unsigned pk2(float a, float b) { f32x2 v = {a, b}; bf2_t r = __builtin_convertvector(v, bf2_t); return __builtin_bit_cast(unsigned, r); }
; __device__ __forceinline__ void phase_expert(const Params& p, int layer, int row0) {
;     ...
; #pragma unroll
;     for (int c = 0; c < 2; ++c) {
; #pragma unroll
;       for (int q8 = 0; q8 < 2; ++q8) {
;         const int col = c * 1024 + lane2 * 16 + q8 * 8;
;         float o[8];
; #pragma unroll
;         for (int e = 0; e < 8; ++e) o[e] = (pre[c * 16 + q8 * 8 + e] - mu) * rstd * G[col + e] + B[col + e];
;         if (layer == 0) {
;           *(f32x4*)(XR + (size_t)row * LDF + col) = f32x4{o[0], o[1], o[2], o[3]};
;           *(f32x4*)(XR + (size_t)row * LDF + col + 4) = f32x4{o[4], o[5], o[6], o[7]};
;           float z[8];
; #pragma unroll
;           for (int e = 0; e < 8; ++e) z[e] = o[e] * (1.f + mdn[2048 + col + e]) + mdn[col + e];
;           *(u32x4*)(XMo + (size_t)row * LDX + col) = u32x4{pk2(z[0], z[1]), pk2(z[2], z[3]), pk2(z[4], z[5]), pk2(z[6], z[7])};
	v_fma_f32 v36, v44, v30, v26
	v_fma_f32 v37, v45, v31, v27
	v_fma_f32 v26, v48, v32, v28
	v_fma_f32 v27, v49, v33, v29
	s_waitcnt vmcnt(0)
	v_fma_f32 v28, v50, v38, v40
	v_fma_f32 v29, v51, v39, v41
	global_store_dwordx4 v[2:3], v[34:37], off
	global_store_dwordx4 v[6:7], v[26:29], off offset:16
	global_load_dwordx4 v[30:33], v[24:25], off
	global_load_dwordx4 v[38:41], v[42:43], off offset:16
	v_addc_co_u32_e32 v23, vcc, 0, v9, vcc
	global_load_dwordx2 v[6:7], v[22:23], off
	global_load_dwordx4 v[42:45], v[46:47], off
	s_nop 0
	global_load_dwordx2 v[46:47], v[46:47], off offset:16
	v_lshlrev_b64 v[48:49], 2, v[0:1]
	v_lshl_add_u64 v[0:1], s[42:43], 0, v[48:49]
	v_lshl_add_u64 v[50:51], s[44:45], 0, v[48:49]
	v_lshl_add_u64 v[8:9], v[8:9], 0, s[36:37]
	v_cmp_lt_i32_e32 vcc, s66, v215
	s_or_b64 s[4:5], vcc, s[4:5]
	s_waitcnt vmcnt(4)
	v_add_f32_e64 v30, v30, 1.0
	v_add_f32_e64 v31, v31, 1.0
	v_add_f32_e64 v32, v32, 1.0
	v_add_f32_e64 v33, v33, 1.0
	s_waitcnt vmcnt(3)
	v_add_f32_e64 v38, v38, 1.0
	v_add_f32_e64 v39, v39, 1.0
	v_add_f32_e64 v40, v40, 1.0
	v_add_f32_e64 v41, v41, 1.0
	s_waitcnt vmcnt(2)
	v_fma_f32 v6, v34, v30, v6
	v_fma_f32 v7, v35, v31, v7
	s_waitcnt vmcnt(1)
	v_fma_f32 v30, v36, v32, v42
	v_fma_f32 v31, v37, v33, v43
	v_fma_f32 v32, v26, v38, v44
	v_fma_f32 v33, v27, v39, v45
	s_waitcnt vmcnt(0)
	v_fma_f32 v34, v28, v40, v46
	v_fma_f32 v35, v29, v41, v47
	v_cvt_pk_bf16_f32 v26, v6, v7
	v_cvt_pk_bf16_f32 v27, v30, v31
	v_cvt_pk_bf16_f32 v28, v32, v33
	v_cvt_pk_bf16_f32 v29, v34, v35
	global_store_dwordx4 v[18:19], v[26:29], off offset:2048
	global_load_dwordx2 v[6:7], v[56:57], off offset:32
	global_load_dwordx2 v[34:35], v[58:59], off offset:32
	s_nop 0
	global_load_dwordx4 v[26:29], v[50:51], off
	global_load_dwordx4 v[30:33], v[0:1], off
	s_nop 0
	global_load_dwordx2 v[0:1], v[0:1], off offset:16
	s_nop 0
	global_load_dwordx2 v[36:37], v[50:51], off offset:16
	v_lshl_add_u64 v[38:39], v[4:5], 0, s[22:23]
	v_mul_f32_e64 v4, v14, v20
	v_mul_f32_e64 v5, v15, v20
	v_mul_f32_e64 v14, v16, v20
	v_mul_f32_e64 v15, v17, v20
	s_waitcnt vmcnt(4)
	v_fma_f32 v4, v4, v6, v34
	v_fma_f32 v5, v5, v7, v35
	s_waitcnt vmcnt(2)
	v_fma_f32 v6, v14, v30, v26
	v_fma_f32 v7, v15, v31, v27
	v_fma_f32 v10, v10, v32, v28
	v_fma_f32 v11, v11, v33, v29
	s_waitcnt vmcnt(0)
	v_fma_f32 v12, v12, v0, v36
	v_fma_f32 v13, v13, v1, v37
	global_store_dwordx4 v[2:3], v[4:7], off offset:32
	global_store_dwordx4 v[38:39], v[10:13], off offset:16
	global_load_dwordx4 v[0:3], v[24:25], off offset:32
	s_nop 0
	global_load_dwordx4 v[14:17], v[8:9], off offset:16
	v_lshl_add_u64 v[8:9], s[0:1], 0, v[48:49]
	global_load_dwordx2 v[24:25], v[22:23], off offset:32
	s_nop 0
	global_load_dwordx4 v[20:23], v[8:9], off
	s_nop 0
	global_load_dwordx2 v[8:9], v[8:9], off offset:16
	s_waitcnt vmcnt(4)
	v_add_f32_e64 v0, v0, 1.0
	v_add_f32_e64 v1, v1, 1.0
	v_add_f32_e64 v2, v2, 1.0
	v_add_f32_e64 v3, v3, 1.0
	s_waitcnt vmcnt(3)
	v_add_f32_e64 v14, v14, 1.0
	v_add_f32_e64 v15, v15, 1.0
	v_add_f32_e64 v16, v16, 1.0
	v_add_f32_e64 v17, v17, 1.0
	s_waitcnt vmcnt(2)
	v_fma_f32 v0, v4, v0, v24
	v_fma_f32 v1, v5, v1, v25
	s_waitcnt vmcnt(1)
	v_fma_f32 v2, v6, v2, v20
	v_fma_f32 v3, v7, v3, v21
	v_fma_f32 v4, v10, v14, v22
	v_fma_f32 v5, v11, v15, v23
	s_waitcnt vmcnt(0)
	v_fma_f32 v6, v12, v16, v8
	v_fma_f32 v7, v13, v17, v9
	v_cvt_pk_bf16_f32 v0, v0, v1
	v_cvt_pk_bf16_f32 v1, v2, v3
	v_cvt_pk_bf16_f32 v2, v4, v5
	v_cvt_pk_bf16_f32 v3, v6, v7
	global_store_dwordx4 v[18:19], v[0:3], off offset:2064
	s_andn2_b64 exec, exec, s[4:5]
	s_cbranch_execnz .LBB0_1932

; __device__ __forceinline__ void phase_expert(const Params& p, int layer, int row0) {
;     ...
;     for (int i0 = 0; i0 < 128; i0 += 4) {
;       u32x4 ua[4]; u32x2 ub[4];
;       float gk[4];
;       int ek[4];
; #pragma unroll
;       for (int k = 0; k < 4; ++k) {
;         ek[k] = __builtin_amdgcn_readfirstlane(ex[i0 + k]);
;         gk[k] = gt[i0 + k];
;         const unsigned char* up = UB + (size_t)ek[k] * 1536;
;         ua[k] = *(const u32x4*)(up + lane * 16); ub[k] = *(const u32x2*)(up + 1024 + lane * 8);
;       }
;       float dk[4];
; #pragma unroll
;       for (int k = 0; k < 4; ++k) {
;         const u32x6 pk = {ua[k][0], ua[k][1], ua[k][2], ua[k][3], ub[k][0], ub[k][1]};
;         const f32x32 f = __builtin_amdgcn_cvt_scalef32_pk32_f32_fp6(pk, 1.0f);
;         float d0 = 0.f, d1 = 0.f;
; #pragma unroll
;         for (int j = 0; j < 32; j += 2) { d0 += f[j] * u[j]; d1 += f[j + 1] * u[j + 1]; }
;         dk[k] = d0 + d1;
;         __builtin_amdgcn_sched_barrier(0);
;       }
; #pragma unroll
;       for (int k = 0; k < 4; ++k) {
;         const unsigned char* vp = VB + (size_t)ek[k] * 1536;
;         ua[k] = *(const u32x4*)(vp + lane * 16); ub[k] = *(const u32x2*)(vp + 1024 + lane * 8);
;       }
.LBB0_2561:
	s_add_u32 s98, s28, 16
	s_addc_u32 s99, s29, 0
	s_cmp_ge_i32 s42, 0x78
	s_cselect_b32 s98, s28, s98
	s_cselect_b32 s99, s29, s99
	global_load_dwordx4 v[252:255], v139, s[98:99]
	global_load_dwordx4 v[134:137], v222, s[28:29]
	s_waitcnt vmcnt(8)
	v_cvt_scalef32_pk32_f32_fp6 v[0:31], v[226:231], 1.0
	v_fma_f32 v0, v0, v150, 0
	v_fma_f32 v1, v1, v151, 0
	s_nop 0
	v_fma_f32 v0, v2, v152, v0
	v_fma_f32 v1, v3, v153, v1
	s_nop 0
	v_fma_f32 v0, v4, v154, v0
	v_fma_f32 v1, v5, v155, v1
	s_nop 0
	v_fma_f32 v0, v6, v156, v0
	v_fma_f32 v1, v7, v157, v1
	s_nop 0
	v_fma_f32 v0, v8, v144, v0
	v_fma_f32 v1, v9, v145, v1
	s_nop 0
	v_fma_f32 v0, v10, v146, v0
	v_fma_f32 v1, v11, v147, v1
	s_nop 0
	v_fma_f32 v0, v12, v148, v0
	v_fma_f32 v1, v13, v149, v1
	s_nop 0
	v_fma_f32 v0, v14, v158, v0
	v_fma_f32 v1, v15, v159, v1
	s_nop 0
	v_fma_f32 v0, v16, v160, v0
	v_fma_f32 v1, v17, v161, v1
	s_nop 0
	v_fma_f32 v0, v18, v166, v0
	v_fma_f32 v1, v19, v167, v1
	s_nop 0
	v_fma_f32 v0, v20, v170, v0
	v_fma_f32 v1, v21, v171, v1
	s_nop 0
	v_fma_f32 v0, v22, v174, v0
	v_fma_f32 v1, v23, v175, v1
	s_nop 0
	v_fma_f32 v0, v24, v164, v0
	v_fma_f32 v1, v25, v165, v1
	s_nop 0
	v_fma_f32 v0, v26, v168, v0
	v_fma_f32 v1, v27, v169, v1
	s_nop 0
	v_fma_f32 v0, v28, v172, v0
	v_fma_f32 v1, v29, v173, v1
	s_nop 0
	v_fma_f32 v56, v30, v176, v0
	v_fma_f32 v57, v31, v177, v1
	s_waitcnt vmcnt(6)
	v_cvt_scalef32_pk32_f32_fp6 v[0:31], v[232:237], 1.0
	v_fma_f32 v0, v0, v150, 0
	v_fma_f32 v1, v1, v151, 0
	s_nop 0
	v_fma_f32 v0, v2, v152, v0
	v_fma_f32 v1, v3, v153, v1
	s_nop 0
	v_fma_f32 v0, v4, v154, v0
	v_fma_f32 v1, v5, v155, v1
	s_nop 0
	v_fma_f32 v0, v6, v156, v0
	v_fma_f32 v1, v7, v157, v1
	s_nop 0
	v_fma_f32 v0, v8, v144, v0
	v_fma_f32 v1, v9, v145, v1
	s_nop 0
	v_fma_f32 v0, v10, v146, v0
	v_fma_f32 v1, v11, v147, v1
	s_nop 0
	v_fma_f32 v0, v12, v148, v0
	v_fma_f32 v1, v13, v149, v1
	s_nop 0
	v_fma_f32 v0, v14, v158, v0
	v_fma_f32 v1, v15, v159, v1
	s_nop 0
	v_fma_f32 v0, v16, v160, v0
	v_fma_f32 v1, v17, v161, v1
	s_nop 0
	v_fma_f32 v0, v18, v166, v0
	v_fma_f32 v1, v19, v167, v1
	s_nop 0
	v_fma_f32 v0, v20, v170, v0
	v_fma_f32 v1, v21, v171, v1
	s_nop 0
	v_fma_f32 v0, v22, v174, v0
	v_fma_f32 v1, v23, v175, v1
	s_nop 0
	v_fma_f32 v0, v24, v164, v0
	v_fma_f32 v1, v25, v165, v1
	s_nop 0
	v_fma_f32 v0, v26, v168, v0
	v_fma_f32 v1, v27, v169, v1
	s_nop 0
	v_fma_f32 v0, v28, v172, v0
	v_fma_f32 v1, v29, v173, v1
	s_nop 0
	v_fma_f32 v58, v30, v176, v0
	v_fma_f32 v59, v31, v177, v1
	s_waitcnt vmcnt(4)
	v_cvt_scalef32_pk32_f32_fp6 v[0:31], v[240:245], 1.0
	v_fma_f32 v0, v0, v150, 0
	v_fma_f32 v1, v1, v151, 0
	s_nop 0
	v_fma_f32 v0, v2, v152, v0
	v_fma_f32 v1, v3, v153, v1
	s_nop 0
	v_fma_f32 v0, v4, v154, v0
	v_fma_f32 v1, v5, v155, v1
	s_nop 0
	v_fma_f32 v0, v6, v156, v0
	v_fma_f32 v1, v7, v157, v1
	s_nop 0
	v_fma_f32 v0, v8, v144, v0
	v_fma_f32 v1, v9, v145, v1
	s_nop 0
	v_fma_f32 v0, v10, v146, v0
	v_fma_f32 v1, v11, v147, v1
	s_nop 0
	v_fma_f32 v0, v12, v148, v0
	v_fma_f32 v1, v13, v149, v1
	s_nop 0
	v_fma_f32 v0, v14, v158, v0
	v_fma_f32 v1, v15, v159, v1
	s_nop 0
	v_fma_f32 v0, v16, v160, v0
	v_fma_f32 v1, v17, v161, v1
	s_nop 0
	v_fma_f32 v0, v18, v166, v0
	v_fma_f32 v1, v19, v167, v1
	s_nop 0
	v_fma_f32 v0, v20, v170, v0
	v_fma_f32 v1, v21, v171, v1
	s_nop 0
	v_fma_f32 v0, v22, v174, v0
	v_fma_f32 v1, v23, v175, v1
	s_nop 0
	v_fma_f32 v0, v24, v164, v0
	v_fma_f32 v1, v25, v165, v1
	s_nop 0
	v_fma_f32 v0, v26, v168, v0
	v_fma_f32 v1, v27, v169, v1
	s_nop 0
	v_fma_f32 v0, v28, v172, v0
	v_fma_f32 v1, v29, v173, v1
	s_nop 0
	v_fma_f32 v96, v30, v176, v0
	v_fma_f32 v97, v31, v177, v1
	s_waitcnt vmcnt(2)
	v_cvt_scalef32_pk32_f32_fp6 v[0:31], v[246:251], 1.0
	v_fma_f32 v0, v0, v150, 0
	v_fma_f32 v1, v1, v151, 0
	s_nop 0
	v_fma_f32 v0, v2, v152, v0
	v_fma_f32 v1, v3, v153, v1
	s_nop 0
	v_fma_f32 v0, v4, v154, v0
	v_fma_f32 v1, v5, v155, v1
	s_nop 0
	v_fma_f32 v0, v6, v156, v0
	v_fma_f32 v1, v7, v157, v1
	s_nop 0
	v_fma_f32 v0, v8, v144, v0
	v_fma_f32 v1, v9, v145, v1
	s_nop 0
	v_fma_f32 v0, v10, v146, v0
	v_fma_f32 v1, v11, v147, v1
	s_nop 0
	v_fma_f32 v0, v12, v148, v0
	v_fma_f32 v1, v13, v149, v1
	s_nop 0
	v_fma_f32 v0, v14, v158, v0
	v_fma_f32 v1, v15, v159, v1
	s_nop 0
	v_fma_f32 v0, v16, v160, v0
	v_fma_f32 v1, v17, v161, v1
	s_nop 0
	v_fma_f32 v0, v18, v166, v0
	v_fma_f32 v1, v19, v167, v1
	s_nop 0
	v_fma_f32 v0, v20, v170, v0
	v_fma_f32 v1, v21, v171, v1
	s_nop 0
	v_fma_f32 v0, v22, v174, v0
	v_fma_f32 v1, v23, v175, v1
	s_nop 0
	v_fma_f32 v0, v24, v164, v0
	v_fma_f32 v1, v25, v165, v1
	s_nop 0
	v_fma_f32 v0, v26, v168, v0
	v_fma_f32 v1, v27, v169, v1
	s_nop 0
	v_fma_f32 v0, v28, v172, v0
	v_fma_f32 v1, v29, v173, v1
	s_nop 0
	v_fma_f32 v208, v30, v176, v0
	v_fma_f32 v209, v31, v177, v1
	s_add_u32 s48, s17, s44
	s_addc_u32 s49, s23, 0
	v_lshl_add_u64 v[0:1], s[48:49], 0, v[138:139]
	v_lshl_add_u64 v[2:3], s[48:49], 0, v[142:143]
	global_load_dwordx4 v[32:35], v[0:1], off
	global_load_dwordx2 v[36:37], v[2:3], off offset:1024
	s_add_u32 s48, s17, s27
	s_addc_u32 s49, s23, 0
	v_lshl_add_u64 v[0:1], s[48:49], 0, v[138:139]
	v_lshl_add_u64 v[2:3], s[48:49], 0, v[142:143]
	global_load_dwordx4 v[38:41], v[0:1], off
	global_load_dwordx2 v[42:43], v[2:3], off offset:1024
	s_add_u32 s48, s17, s45
	s_addc_u32 s49, s23, 0
	v_lshl_add_u64 v[0:1], s[48:49], 0, v[138:139]
	v_lshl_add_u64 v[2:3], s[48:49], 0, v[142:143]
	global_load_dwordx4 v[98:101], v[0:1], off
	global_load_dwordx2 v[102:103], v[2:3], off offset:1024
	s_add_u32 s48, s17, s47
	s_addc_u32 s49, s23, 0
	v_lshl_add_u64 v[0:1], s[48:49], 0, v[138:139]
	v_lshl_add_u64 v[2:3], s[48:49], 0, v[142:143]
	global_load_dwordx4 v[128:131], v[0:1], off
	global_load_dwordx2 v[132:133], v[2:3], off offset:1024
	s_waitcnt vmcnt(9)
; __device__ __forceinline__ void phase_expert(const Params& p, int layer, int row0) {
;     ...
; #pragma unroll
;       for (int k = 0; k < 4; ++k) {
;         ek[k] = __builtin_amdgcn_readfirstlane(ex[i0 + k]);
;         gk[k] = gt[i0 + k];
;         const unsigned char* up = UB + (size_t)ek[k] * 1536;
;         ua[k] = *(const u32x4*)(up + lane * 16); ub[k] = *(const u32x2*)(up + 1024 + lane * 8);
;     ...
; #pragma unroll
;       for (int o = 32; o >= 1; o >>= 1) {
; #pragma unroll
;         for (int k = 0; k < 4; ++k) dk[k] += __shfl_xor(dk[k], o);
;       }
; #pragma unroll
;       for (int k = 0; k < 4; ++k) {
;         const float a = dk[k] * (1.f / SC_U);
;         const float w = gk[k] * (0.5f * a * (1.f + my_erf(a * 0.7071067811865476f)));
;         const u32x6 pk = {ua[k][0], ua[k][1], ua[k][2], ua[k][3], ub[k][0], ub[k][1]};
;         const f32x32 f = __builtin_amdgcn_cvt_scalef32_pk32_f32_fp6(pk, 1.0f);
; #pragma unroll
;         for (int j = 0; j < 32; ++j) y[j] += w * f[j];
;         __builtin_amdgcn_sched_barrier(0);
;       }
	v_readfirstlane_b32 s44, v252
	v_readfirstlane_b32 s27, v253
	v_readfirstlane_b32 s45, v254
	v_readfirstlane_b32 s47, v255
	s_mulk_i32 s44, 0x600
	s_mulk_i32 s27, 0x600
	s_mulk_i32 s45, 0x600
	s_mulk_i32 s47, 0x600
	s_add_u32 s48, s11, s44
	s_addc_u32 s49, s13, 0
	v_lshl_add_u64 v[0:1], s[48:49], 0, v[138:139]
	v_lshl_add_u64 v[2:3], s[48:49], 0, v[142:143]
	global_load_dwordx4 v[226:229], v[0:1], off
	global_load_dwordx2 v[230:231], v[2:3], off offset:1024
	s_add_u32 s48, s11, s27
	s_addc_u32 s49, s13, 0
	v_lshl_add_u64 v[0:1], s[48:49], 0, v[138:139]
	v_lshl_add_u64 v[2:3], s[48:49], 0, v[142:143]
	global_load_dwordx4 v[232:235], v[0:1], off
	global_load_dwordx2 v[236:237], v[2:3], off offset:1024
	s_add_u32 s48, s11, s45
	s_addc_u32 s49, s13, 0
	v_lshl_add_u64 v[0:1], s[48:49], 0, v[138:139]
	v_lshl_add_u64 v[2:3], s[48:49], 0, v[142:143]
	global_load_dwordx4 v[240:243], v[0:1], off
	global_load_dwordx2 v[244:245], v[2:3], off offset:1024
	s_add_u32 s48, s11, s47
	s_addc_u32 s49, s13, 0
	v_lshl_add_u64 v[0:1], s[48:49], 0, v[138:139]
	v_lshl_add_u64 v[2:3], s[48:49], 0, v[142:143]
	global_load_dwordx4 v[246:249], v[0:1], off
	global_load_dwordx2 v[250:251], v[2:3], off offset:1024
	s_waitcnt vmcnt(14)
	v_cvt_scalef32_pk32_f32_fp6 v[0:31], v[32:37], 1.0
	v_mov_b32_e32 v32, v59
	v_mov_b32_e32 v33, v57
	v_mov_b32_e32 v59, v56
	v_add_f32_e64 v32, v32, v58
	v_add_f32_e64 v33, v33, v59
	ds_bpermute_b32 v35, v216, v33
	ds_bpermute_b32 v34, v216, v32
	s_waitcnt vmcnt(12)
	v_cvt_scalef32_pk32_f32_fp6 v[64:95], v[38:43], 1.0
	s_waitcnt lgkmcnt(0)
	v_add_f32_e64 v32, v32, v34
	v_add_f32_e64 v33, v33, v35
	ds_bpermute_b32 v35, v217, v33
	ds_bpermute_b32 v34, v217, v32
	s_waitcnt lgkmcnt(0)
	v_add_f32_e64 v32, v32, v34
	v_add_f32_e64 v33, v33, v35
	ds_bpermute_b32 v35, v218, v33
	ds_bpermute_b32 v34, v218, v32
	s_waitcnt lgkmcnt(0)
	v_add_f32_e64 v32, v32, v34
	v_add_f32_e64 v33, v33, v35
	ds_bpermute_b32 v35, v219, v33
	ds_bpermute_b32 v34, v219, v32
	s_waitcnt lgkmcnt(0)
	v_add_f32_e64 v32, v32, v34
	v_add_f32_e64 v33, v33, v35
	ds_bpermute_b32 v35, v220, v33
	ds_bpermute_b32 v34, v220, v32
	s_waitcnt lgkmcnt(0)
	v_add_f32_e64 v32, v32, v34
	v_add_f32_e64 v33, v33, v35
	ds_bpermute_b32 v35, v214, v33
	ds_bpermute_b32 v34, v214, v32
	s_waitcnt lgkmcnt(0)
	v_add_f32_e64 v32, v32, v34
	v_add_f32_e64 v33, v33, v35
	s_nop 0
	v_mul_f32_e64 v32, v32, s10
	v_mul_f32_e64 v33, v33, s10
	s_nop 0
	v_mul_f32_e64 v34, v32, s12
	v_mul_f32_e64 v35, v33, s12
	v_mul_f32_e32 v36, 0.5, v33
	v_fma_f32 v33, |v35|, s36, 1.0
	v_div_scale_f32 v45, s[0:1], v33, v33, 1.0
	v_rcp_f32_e32 v48, v45
	v_div_scale_f32 v46, vcc, 1.0, v33, 1.0
	v_mul_f32_e64 v37, |v35|, -|v35|
	v_fma_f32 v51, -v45, v48, 1.0
	v_fmac_f32_e32 v48, v51, v48
	v_mul_f32_e32 v51, v46, v48
	v_fma_f32 v53, -v45, v51, v46
	v_fmac_f32_e32 v51, v53, v48
	v_fma_f32 v45, -v45, v51, v46
	v_div_fmas_f32 v45, v45, v48, v51
	v_div_fixup_f32 v33, v45, v33, 1.0
	v_fma_f32 v44, |v34|, s36, 1.0
	v_mul_f32_e32 v37, 0x3fb8aa3b, v37
	v_fmamk_f32 v45, v33, 0x3f87dc22, v223
	v_div_scale_f32 v47, s[0:1], v44, v44, 1.0
	v_exp_f32_e32 v37, v37
	v_fmaak_f32 v45, v33, v45, 0x3fb5f0e3
	v_rcp_f32_e32 v49, v47
	v_fmaak_f32 v45, v33, v45, 0xbe91a98e
	v_fmaak_f32 v45, v33, v45, 0x3e827906
	v_mul_f32_e32 v33, v33, v45
	v_fma_f32 v33, -v37, v33, 1.0
	v_cmp_gt_f32_e32 vcc, 0, v35
	v_fma_f32 v52, -v47, v49, 1.0
	v_div_scale_f32 v50, s[0:1], 1.0, v44, 1.0
	v_cndmask_b32_e64 v33, v33, -v33, vcc
	v_fmac_f32_e32 v49, v52, v49
	v_add_f32_e32 v33, 1.0, v33
	v_mul_f32_e32 v52, v50, v49
	v_mul_f32_e32 v33, v36, v33
	v_mul_f32_e32 v134, v134, v33
	v_fma_f32 v33, -v47, v52, v50
	v_fmac_f32_e32 v52, v33, v49
	v_fma_f32 v33, -v47, v52, v50
	s_mov_b64 vcc, s[0:1]
	v_div_fmas_f32 v33, v33, v49, v52
	v_div_fixup_f32 v33, v33, v44, 1.0
	v_mul_f32_e64 v36, |v34|, -|v34|
	v_fmamk_f32 v35, v33, 0x3f87dc22, v223
	v_mul_f32_e32 v36, 0x3fb8aa3b, v36
	v_fmaak_f32 v35, v33, v35, 0x3fb5f0e3
	v_exp_f32_e32 v36, v36
	v_fmaak_f32 v35, v33, v35, 0xbe91a98e
	v_fmaak_f32 v35, v33, v35, 0x3e827906
	v_mul_f32_e32 v33, v33, v35
	v_fma_f32 v33, -v36, v33, 1.0
	v_cmp_gt_f32_e32 vcc, 0, v34
	v_mul_f32_e32 v32, 0.5, v32
	s_nop 0
	v_cndmask_b32_e64 v33, v33, -v33, vcc
	v_add_f32_e32 v33, 1.0, v33
	v_mul_f32_e32 v32, v32, v33
	v_mul_f32_e32 v210, v135, v32
	s_waitcnt vmcnt(10)
	v_cvt_scalef32_pk32_f32_fp6 v[32:63], v[98:103], 1.0
	v_mov_b32_e32 v212, v209
	v_mov_b32_e32 v213, v97
	v_mov_b32_e32 v209, v96
	s_waitcnt vmcnt(8)
	v_cvt_scalef32_pk32_f32_fp6 v[96:127], v[128:133], 1.0
	v_fma_f32 v0, v0, v134, v206
	v_fma_f32 v1, v1, v134, v207
	v_add_f32_e64 v128, v212, v208
	v_add_f32_e64 v129, v213, v209
	v_fma_f32 v0, v64, v210, v0
	v_fma_f32 v1, v65, v210, v1
	ds_bpermute_b32 v65, v216, v129
	ds_bpermute_b32 v64, v216, v128
	v_fma_f32 v2, v2, v134, v204
	v_fma_f32 v3, v3, v134, v205
	v_fma_f32 v4, v4, v134, v202
	v_fma_f32 v5, v5, v134, v203
	v_fma_f32 v2, v66, v210, v2
	v_fma_f32 v3, v67, v210, v3
	v_fma_f32 v6, v6, v134, v200
	v_fma_f32 v7, v7, v134, v201
	s_waitcnt lgkmcnt(0)
	v_add_f32_e64 v64, v128, v64
	v_add_f32_e64 v65, v129, v65
	ds_bpermute_b32 v67, v217, v65
	ds_bpermute_b32 v66, v217, v64
	v_fma_f32 v8, v8, v134, v198
	v_fma_f32 v9, v9, v134, v199
	v_fma_f32 v4, v68, v210, v4
	v_fma_f32 v5, v69, v210, v5
	v_fma_f32 v10, v10, v134, v196
	v_fma_f32 v11, v11, v134, v197
	v_fma_f32 v12, v12, v134, v194
	v_fma_f32 v13, v13, v134, v195
	s_waitcnt lgkmcnt(0)
	v_add_f32_e64 v64, v64, v66
	v_add_f32_e64 v65, v65, v67
	ds_bpermute_b32 v67, v218, v65
	ds_bpermute_b32 v66, v218, v64
	v_fma_f32 v6, v70, v210, v6
	v_fma_f32 v7, v71, v210, v7
	v_fma_f32 v8, v72, v210, v8
	v_fma_f32 v9, v73, v210, v9
	v_fma_f32 v10, v74, v210, v10
	v_fma_f32 v11, v75, v210, v11
	v_fma_f32 v12, v76, v210, v12
	v_fma_f32 v13, v77, v210, v13
	s_waitcnt lgkmcnt(0)
; __device__ __forceinline__ void phase_expert(const Params& p, int layer, int row0) {
;     ...
; #pragma unroll
;       for (int o = 32; o >= 1; o >>= 1) {
; #pragma unroll
;         for (int k = 0; k < 4; ++k) dk[k] += __shfl_xor(dk[k], o);
;       }
; #pragma unroll
;       for (int k = 0; k < 4; ++k) {
;         const float a = dk[k] * (1.f / SC_U);
;         const float w = gk[k] * (0.5f * a * (1.f + my_erf(a * 0.7071067811865476f)));
;         const u32x6 pk = {ua[k][0], ua[k][1], ua[k][2], ua[k][3], ub[k][0], ub[k][1]};
;         const f32x32 f = __builtin_amdgcn_cvt_scalef32_pk32_f32_fp6(pk, 1.0f);
; #pragma unroll
;         for (int j = 0; j < 32; ++j) y[j] += w * f[j];
;         __builtin_amdgcn_sched_barrier(0);
;       }
	v_add_f32_e64 v64, v64, v66
	v_add_f32_e64 v65, v65, v67
	ds_bpermute_b32 v67, v219, v65
	ds_bpermute_b32 v66, v219, v64
	v_fma_f32 v14, v14, v134, v192
	v_fma_f32 v15, v15, v134, v193
	v_fma_f32 v16, v16, v134, v190
	v_fma_f32 v17, v17, v134, v191
	v_fma_f32 v14, v78, v210, v14
	v_fma_f32 v15, v79, v210, v15
	v_fma_f32 v16, v80, v210, v16
	v_fma_f32 v17, v81, v210, v17
	s_waitcnt lgkmcnt(0)
	v_add_f32_e64 v64, v64, v66
	v_add_f32_e64 v65, v65, v67
	ds_bpermute_b32 v67, v220, v65
	ds_bpermute_b32 v66, v220, v64
	v_fma_f32 v18, v18, v134, v188
	v_fma_f32 v19, v19, v134, v189
	v_fma_f32 v20, v20, v134, v186
	v_fma_f32 v21, v21, v134, v187
	v_fma_f32 v22, v22, v134, v184
	v_fma_f32 v23, v23, v134, v185
	v_fma_f32 v24, v24, v134, v182
	v_fma_f32 v25, v25, v134, v183
	s_waitcnt lgkmcnt(0)
	v_add_f32_e64 v64, v64, v66
	v_add_f32_e64 v65, v65, v67
	ds_bpermute_b32 v67, v214, v65
	ds_bpermute_b32 v66, v214, v64
	v_fma_f32 v26, v26, v134, v180
	v_fma_f32 v27, v27, v134, v181
	v_fma_f32 v28, v28, v134, v178
	v_fma_f32 v29, v29, v134, v179
	v_fma_f32 v30, v30, v134, v162
	v_fma_f32 v31, v31, v134, v163
	v_fma_f32 v18, v82, v210, v18
	v_fma_f32 v19, v83, v210, v19
	s_waitcnt lgkmcnt(0)
	v_add_f32_e64 v64, v64, v66
	v_add_f32_e64 v65, v65, v67
	v_fma_f32 v20, v84, v210, v20
	v_fma_f32 v21, v85, v210, v21
	v_mul_f32_e64 v64, v64, s10
	v_mul_f32_e64 v65, v65, s10
	v_fma_f32 v22, v86, v210, v22
	v_fma_f32 v23, v87, v210, v23
	v_mul_f32_e64 v66, v64, s12
	v_mul_f32_e64 v67, v65, s12
	v_mul_f32_e32 v68, 0.5, v65
	v_mul_f32_e32 v65, 0.5, v64
	v_fma_f32 v64, |v67|, s36, 1.0
	v_fma_f32 v70, |v66|, s36, 1.0
	v_div_scale_f32 v72, s[0:1], v64, v64, 1.0
	v_div_scale_f32 v74, s[0:1], v70, v70, 1.0
	v_rcp_f32_e32 v76, v72
	v_rcp_f32_e32 v77, v74
	v_div_scale_f32 v73, vcc, 1.0, v64, 1.0
	v_fma_f32 v78, -v72, v76, 1.0
	v_fma_f32 v79, -v74, v77, 1.0
	v_fmac_f32_e32 v76, v78, v76
	v_div_scale_f32 v75, s[0:1], 1.0, v70, 1.0
	v_fmac_f32_e32 v77, v79, v77
	v_mul_f32_e32 v78, v73, v76
	v_mul_f32_e32 v79, v75, v77
	v_fma_f32 v80, -v72, v78, v73
	v_fma_f32 v81, -v74, v79, v75
	v_fmac_f32_e32 v78, v80, v76
	v_fmac_f32_e32 v79, v81, v77
	v_fma_f32 v72, -v72, v78, v73
	v_fma_f32 v73, -v74, v79, v75
	v_div_fmas_f32 v72, v72, v76, v78
	s_mov_b64 vcc, s[0:1]
	v_mul_f32_e64 v69, |v67|, -|v67|
	v_div_fixup_f32 v64, v72, v64, 1.0
	v_div_fmas_f32 v72, v73, v77, v79
	v_mul_f32_e64 v71, |v66|, -|v66|
	v_mul_f32_e32 v69, 0x3fb8aa3b, v69
	v_fmamk_f32 v73, v64, 0x3f87dc22, v223
	v_div_fixup_f32 v70, v72, v70, 1.0
	v_mul_f32_e32 v71, 0x3fb8aa3b, v71
	v_exp_f32_e32 v69, v69
	v_fmaak_f32 v72, v64, v73, 0x3fb5f0e3
	v_fmamk_f32 v73, v70, 0x3f87dc22, v223
	v_exp_f32_e32 v71, v71
	v_fmaak_f32 v72, v64, v72, 0xbe91a98e
	v_fmaak_f32 v73, v70, v73, 0x3fb5f0e3
	v_fmaak_f32 v72, v64, v72, 0x3e827906
	v_fmaak_f32 v73, v70, v73, 0xbe91a98e
	v_mul_f32_e32 v64, v64, v72
	v_fmaak_f32 v72, v70, v73, 0x3e827906
	v_fma_f32 v64, -v69, v64, 1.0
	v_cmp_gt_f32_e32 vcc, 0, v67
	v_mul_f32_e32 v67, v70, v72
	v_fma_f32 v67, -v71, v67, 1.0
	v_cmp_gt_f32_e64 s[0:1], 0, v66
	v_cndmask_b32_e64 v64, v64, -v64, vcc
	v_add_f32_e32 v64, 1.0, v64
	v_cndmask_b32_e64 v66, v67, -v67, s[0:1]
	v_mul_f32_e32 v64, v68, v64
	v_add_f32_e32 v66, 1.0, v66
	v_fma_f32 v24, v88, v210, v24
	v_fma_f32 v25, v89, v210, v25
	v_fma_f32 v26, v90, v210, v26
	v_fma_f32 v27, v91, v210, v27
	v_fma_f32 v28, v92, v210, v28
	v_fma_f32 v29, v93, v210, v29
	v_fma_f32 v30, v94, v210, v30
	v_fma_f32 v31, v95, v210, v31
	v_mul_f32_e32 v64, v136, v64
	v_mul_f32_e32 v65, v65, v66
	v_mul_f32_e32 v66, v137, v65
	v_fma_f32 v0, v32, v64, v0
	v_fma_f32 v1, v33, v64, v1
	v_fma_f32 v2, v34, v64, v2
	v_fma_f32 v3, v35, v64, v3
	v_fma_f32 v4, v36, v64, v4
	v_fma_f32 v5, v37, v64, v5
	v_fma_f32 v6, v38, v64, v6
	v_fma_f32 v7, v39, v64, v7
	v_fma_f32 v8, v40, v64, v8
	v_fma_f32 v9, v41, v64, v9
	v_fma_f32 v10, v42, v64, v10
	v_fma_f32 v11, v43, v64, v11
	v_fma_f32 v12, v44, v64, v12
	v_fma_f32 v13, v45, v64, v13
	v_fma_f32 v14, v46, v64, v14
	v_fma_f32 v15, v47, v64, v15
	v_fma_f32 v16, v48, v64, v16
	v_fma_f32 v17, v49, v64, v17
	v_fma_f32 v18, v50, v64, v18
	v_fma_f32 v19, v51, v64, v19
	v_fma_f32 v20, v52, v64, v20
	v_fma_f32 v21, v53, v64, v21
	v_fma_f32 v22, v54, v64, v22
	v_fma_f32 v23, v55, v64, v23
	v_fma_f32 v24, v56, v64, v24
	v_fma_f32 v25, v57, v64, v25
	v_fma_f32 v26, v58, v64, v26
	v_fma_f32 v27, v59, v64, v27
	v_fma_f32 v28, v60, v64, v28
	v_fma_f32 v29, v61, v64, v29
	v_fma_f32 v30, v62, v64, v30
	v_fma_f32 v31, v63, v64, v31
	v_fma_f32 v206, v96, v66, v0
	v_fma_f32 v207, v97, v66, v1
	v_fma_f32 v204, v98, v66, v2
	v_fma_f32 v205, v99, v66, v3
	v_fma_f32 v202, v100, v66, v4
	v_fma_f32 v203, v101, v66, v5
	v_fma_f32 v200, v102, v66, v6
	v_fma_f32 v201, v103, v66, v7
	v_fma_f32 v198, v104, v66, v8
	v_fma_f32 v199, v105, v66, v9
	v_fma_f32 v196, v106, v66, v10
	v_fma_f32 v197, v107, v66, v11
	v_fma_f32 v194, v108, v66, v12
	v_fma_f32 v195, v109, v66, v13
	v_fma_f32 v192, v110, v66, v14
	v_fma_f32 v193, v111, v66, v15
	v_fma_f32 v190, v112, v66, v16
	v_fma_f32 v191, v113, v66, v17
	v_fma_f32 v188, v114, v66, v18
	v_fma_f32 v189, v115, v66, v19
	v_fma_f32 v186, v116, v66, v20
	v_fma_f32 v187, v117, v66, v21
	v_fma_f32 v184, v118, v66, v22
	v_fma_f32 v185, v119, v66, v23
	v_fma_f32 v182, v120, v66, v24
	v_fma_f32 v183, v121, v66, v25
	v_fma_f32 v180, v122, v66, v26
	v_fma_f32 v181, v123, v66, v27
	v_fma_f32 v178, v124, v66, v28
	v_fma_f32 v179, v125, v66, v29
	v_fma_f32 v162, v126, v66, v30
	v_fma_f32 v163, v127, v66, v31
	s_add_i32 s42, s42, 4
	s_add_u32 s28, s28, 16
	s_addc_u32 s29, s29, 0
	s_cmpk_gt_u32 s42, 0x7b
	s_cbranch_scc0 .LBB0_2561
; DI const float* modp(const Params& p, int layer, int v) { return (const float*)(p.ws + OFF_MOD) + (size_t)(layer * 2 + v) * 12288; }
; __device__ __forceinline__ void phase_expert(const Params& p, int layer, int row0) {
;     ...
;     int lane2 = lane; asm volatile("" : "+v"(lane2));
;     const int v = row < NCTX ? 1 : 0;
;     const float* md = modp(p, layer, v);
;     float pre[32];
;     float s = 0.f;
; #pragma unroll
;     for (int c = 0; c < 2; ++c) {
; #pragma unroll
;       for (int q4 = 0; q4 < 4; ++q4) {
;         const int col = c * 1024 + lane2 * 16 + q4 * 4;
;         const f32x4 a = *(const f32x4*)(XR + (size_t)row * LDF + col);
;         const f32x4 g2 = *(const f32x4*)(md + 10240 + col);
; #pragma unroll
;         for (int e = 0; e < 4; ++e) {
;           const float pv = ALPHA * a[e] + g2[e] * (y[c * 16 + q4 * 4 + e] * (1.f / SC_V));
;           pre[c * 16 + q4 * 4 + e] = pv; s += pv;
;         }
;       }
;     }
;     const float mu = wave_sum(s) * (1.f / 2048.f);
	v_mov_b32_e32 v0, v211
	s_cmpk_lt_i32 s26, 0x100
	s_cselect_b32 s0, s37, 0x18000
	v_lshlrev_b32_e32 v0, 4, v0
	s_add_u32 s0, s4, s0
	v_ashrrev_i32_e32 v1, 31, v0
	s_addc_u32 s1, s5, 0
	v_lshlrev_b64 v[2:3], 2, v[0:1]
	v_lshl_add_u64 v[16:17], s[0:1], 0, v[2:3]
	s_mul_i32 s0, s26, 0x2080
	v_add_co_u32_e32 v30, vcc, s39, v16
	s_mul_hi_i32 s1, s26, 0x2080
	s_add_u32 s0, s33, s0
	v_lshl_add_u64 v[28:29], v[16:17], 0, s[14:15]
	v_lshl_add_u64 v[56:57], v[16:17], 0, s[20:21]
	v_addc_co_u32_e32 v31, vcc, 0, v17, vcc
	s_addc_u32 s1, s34, s1
	global_load_dwordx4 v[4:7], v[28:29], off offset:32
	global_load_dwordx4 v[8:11], v[28:29], off offset:16
	global_load_dwordx4 v[12:15], v[56:57], off offset:48
	global_load_dwordx4 v[16:19], v[30:31], off offset:-4096
	global_load_dwordx4 v[20:23], v[56:57], off offset:32
	global_load_dwordx4 v[24:27], v[28:29], off offset:48
	v_lshl_add_u64 v[58:59], s[0:1], 0, v[2:3]
	v_lshl_add_u64 v[68:69], v[58:59], 0, s[18:19]
	global_load_dwordx4 v[28:31], v[30:31], off
	s_nop 0
	global_load_dwordx4 v[32:35], v[68:69], off offset:48
	global_load_dwordx4 v[36:39], v[58:59], off offset:16
	global_load_dwordx4 v[40:43], v[58:59], off
	global_load_dwordx4 v[44:47], v[58:59], off offset:32
	global_load_dwordx4 v[48:51], v[58:59], off offset:48
	global_load_dwordx4 v[52:55], v[56:57], off offset:16
	v_add_co_u32_e32 v70, vcc, s38, v58
	v_mul_f32_e64 v72, v202, s16
	v_mul_f32_e64 v73, v203, s16
	s_nop 0
	v_addc_co_u32_e32 v71, vcc, 0, v59, vcc
	global_load_dwordx4 v[56:59], v[70:71], off
	global_load_dwordx4 v[60:63], v[68:69], off offset:32
	global_load_dwordx4 v[64:67], v[68:69], off offset:16
	v_mul_f32_e64 v68, v206, s16
	v_mul_f32_e64 v69, v207, s16
	v_mul_f32_e64 v70, v204, s16
	v_mul_f32_e64 v71, v205, s16
	v_mul_f32_e64 v74, v200, s16
	v_mul_f32_e64 v75, v201, s16
	v_mul_f32_e64 v76, v198, s16
	v_mul_f32_e64 v77, v199, s16
	v_mul_f32_e64 v78, v196, s16
	v_mul_f32_e64 v79, v197, s16
	v_mul_f32_e64 v80, v194, s16
	v_mul_f32_e64 v81, v195, s16
	v_mul_f32_e64 v82, v192, s16
	v_mul_f32_e64 v83, v193, s16
	v_mul_f32_e64 v84, v190, s16
	v_mul_f32_e64 v85, v191, s16
	v_mul_f32_e64 v86, v188, s16
	v_mul_f32_e64 v87, v189, s16
	v_mul_f32_e64 v88, v186, s16
	v_mul_f32_e64 v89, v187, s16
	v_mul_f32_e64 v90, v184, s16
	v_mul_f32_e64 v91, v185, s16
	v_mul_f32_e64 v92, v182, s16
	v_mul_f32_e64 v93, v183, s16
	v_mul_f32_e64 v94, v180, s16
	v_mul_f32_e64 v95, v181, s16
	v_mul_f32_e64 v96, v178, s16
	v_mul_f32_e64 v97, v179, s16
	v_mul_f32_e64 v98, v162, s16
	v_mul_f32_e64 v99, v163, s16
	s_add_i32 s0, s26, 0xffffff00
	s_ashr_i32 s1, s0, 31
	s_lshl_b64 s[0:1], s[0:1], 13
	s_add_u32 s0, s84, s0
	s_addc_u32 s1, s85, s1
	v_add_u32_e32 v215, s35, v215
	s_waitcnt vmcnt(15)
	v_mul_f32_e64 v4, v76, v4
	v_mul_f32_e64 v5, v77, v5
	s_waitcnt vmcnt(12)
	v_mul_f32_e64 v16, v68, v16
	v_mul_f32_e64 v17, v69, v17
	v_mul_f32_e64 v18, v70, v18
	v_mul_f32_e64 v19, v71, v19
	v_mul_f32_e64 v8, v72, v8
	v_mul_f32_e64 v9, v73, v9
	s_waitcnt vmcnt(6)
	v_fma_f32 v40, v40, s22, v16
	v_fma_f32 v41, v41, s22, v17
	v_fma_f32 v42, v42, s22, v18
	v_fma_f32 v43, v43, s22, v19
	v_add_f32_e32 v1, 0, v40
	v_add_f32_e32 v1, v41, v1
	v_add_f32_e32 v1, v42, v1
	v_fma_f32 v36, v36, s22, v8
	v_fma_f32 v37, v37, s22, v9
	v_add_f32_e32 v1, v43, v1
	v_mul_f32_e64 v10, v74, v10
	v_mul_f32_e64 v11, v75, v11
	v_add_f32_e32 v1, v36, v1
	v_fma_f32 v38, v38, s22, v10
	v_fma_f32 v39, v39, s22, v11
	v_add_f32_e32 v1, v37, v1
	v_add_f32_e32 v1, v38, v1
	s_waitcnt vmcnt(5)
	v_fma_f32 v44, v44, s22, v4
	v_fma_f32 v45, v45, s22, v5
	v_add_f32_e32 v1, v39, v1
	v_mul_f32_e64 v6, v78, v6
	v_mul_f32_e64 v7, v79, v7
	v_add_f32_e32 v1, v44, v1
	v_fma_f32 v46, v46, s22, v6
	v_fma_f32 v47, v47, s22, v7
	v_add_f32_e32 v1, v45, v1
	v_mul_f32_e64 v24, v80, v24
	v_mul_f32_e64 v25, v81, v25
	v_add_f32_e32 v1, v46, v1
	s_waitcnt vmcnt(4)
	v_fma_f32 v24, v48, s22, v24
	v_fma_f32 v25, v49, s22, v25
	v_add_f32_e32 v1, v47, v1
	v_mul_f32_e64 v26, v82, v26
	v_mul_f32_e64 v27, v83, v27
	v_add_f32_e32 v1, v24, v1
	v_fma_f32 v26, v50, s22, v26
	v_fma_f32 v27, v51, s22, v27
	v_add_f32_e32 v1, v25, v1
	v_mul_f32_e64 v28, v84, v28
	v_mul_f32_e64 v29, v85, v29
	v_add_f32_e32 v1, v26, v1
	s_waitcnt vmcnt(2)
	v_fma_f32 v28, v56, s22, v28
	v_fma_f32 v29, v57, s22, v29
	v_add_f32_e32 v1, v27, v1
	v_mul_f32_e64 v30, v86, v30
	v_mul_f32_e64 v31, v87, v31
	v_add_f32_e32 v1, v28, v1
	v_fma_f32 v30, v58, s22, v30
	v_fma_f32 v31, v59, s22, v31
	v_add_f32_e32 v1, v29, v1
	v_mul_f32_e64 v4, v88, v52
	v_mul_f32_e64 v5, v89, v53
	v_add_f32_e32 v1, v30, v1
	s_waitcnt vmcnt(0)
	v_fma_f32 v48, v64, s22, v4
	v_fma_f32 v49, v65, s22, v5
	v_add_f32_e32 v1, v31, v1
	v_mul_f32_e64 v6, v90, v54
	v_mul_f32_e64 v7, v91, v55
	v_add_f32_e32 v1, v48, v1
	v_fma_f32 v50, v66, s22, v6
	v_fma_f32 v51, v67, s22, v7
	v_add_f32_e32 v1, v49, v1
	v_mul_f32_e64 v20, v92, v20
	v_mul_f32_e64 v21, v93, v21
	v_add_f32_e32 v1, v50, v1
	v_fma_f32 v20, v60, s22, v20
	v_fma_f32 v21, v61, s22, v21
	v_add_f32_e32 v1, v51, v1
	v_mul_f32_e64 v22, v94, v22
	v_mul_f32_e64 v23, v95, v23
	v_add_f32_e32 v1, v20, v1
	v_add_f32_e32 v1, v21, v1
	v_fma_f32 v22, v62, s22, v22
	v_fma_f32 v23, v63, s22, v23
	v_mul_f32_e64 v12, v96, v12
	v_mul_f32_e64 v13, v97, v13
	v_add_f32_e32 v1, v22, v1
	v_fma_f32 v32, v32, s22, v12
	v_fma_f32 v33, v33, s22, v13
	v_add_f32_e32 v1, v23, v1
	v_mul_f32_e64 v14, v98, v14
	v_mul_f32_e64 v15, v99, v15
	v_add_f32_e32 v1, v32, v1
	v_fma_f32 v34, v34, s22, v14
	v_fma_f32 v35, v35, s22, v15
	v_add_f32_e32 v1, v33, v1
	v_add_f32_e32 v1, v34, v1
	v_add_f32_e32 v1, v35, v1
	ds_bpermute_b32 v4, v216, v1
	v_lshl_add_u64 v[52:53], s[6:7], 0, v[2:3]
	v_lshl_add_u64 v[54:55], s[8:9], 0, v[2:3]
	s_waitcnt lgkmcnt(0)
; __device__ __forceinline__ void phase_expert(const Params& p, int layer, int row0) {
;     ...
;     const float mu = wave_sum(s) * (1.f / 2048.f);
;     float q = 0.f;
; #pragma unroll
;     for (int e = 0; e < 32; ++e) { float d = pre[e] - mu; q += d * d; }
;     const float rstd = rsqrtf(wave_sum(q) * (1.f / 2048.f) + LN_EPS);
	v_add_f32_e32 v1, v1, v4
	ds_bpermute_b32 v4, v217, v1
	s_waitcnt lgkmcnt(0)
	v_add_f32_e32 v1, v1, v4
	ds_bpermute_b32 v4, v218, v1
	s_waitcnt lgkmcnt(0)
	v_add_f32_e32 v1, v1, v4
	ds_bpermute_b32 v4, v219, v1
	s_waitcnt lgkmcnt(0)
	v_add_f32_e32 v1, v1, v4
	ds_bpermute_b32 v4, v220, v1
	s_waitcnt lgkmcnt(0)
	v_add_f32_e32 v1, v1, v4
	ds_bpermute_b32 v56, v214, v1
	global_load_dwordx4 v[4:7], v[52:53], off offset:16
	global_load_dwordx4 v[8:11], v[52:53], off
	global_load_dwordx4 v[12:15], v[54:55], off offset:16
	global_load_dwordx4 v[16:19], v[54:55], off
	s_waitcnt lgkmcnt(0)
	v_add_f32_e32 v1, v1, v56
	v_mul_f32_e32 v56, 0x3a000000, v1
	v_add_f32_e64 v40, v40, -v56
	v_add_f32_e64 v41, v41, -v56
	v_add_f32_e64 v42, v42, -v56
	v_add_f32_e64 v43, v43, -v56
	v_mul_f32_e64 v58, v40, v40
	v_mul_f32_e64 v59, v41, v41
	v_mul_f32_e64 v60, v42, v42
	v_mul_f32_e64 v61, v43, v43
	v_add_f32_e32 v1, v58, v59
	v_add_f32_e64 v36, v36, -v56
	v_add_f32_e64 v37, v37, -v56
	v_add_f32_e32 v1, v60, v1
	v_mul_f32_e64 v62, v36, v36
	v_mul_f32_e64 v63, v37, v37
	v_add_f32_e32 v1, v61, v1
	v_add_f32_e64 v38, v38, -v56
	v_add_f32_e64 v39, v39, -v56
	v_add_f32_e32 v1, v62, v1
	v_mul_f32_e64 v64, v38, v38
	v_mul_f32_e64 v65, v39, v39
	v_add_f32_e32 v1, v63, v1
	v_add_f32_e64 v44, v44, -v56
	v_add_f32_e64 v45, v45, -v56
	v_add_f32_e32 v1, v64, v1
	v_mul_f32_e64 v66, v44, v44
	v_mul_f32_e64 v67, v45, v45
	v_add_f32_e32 v1, v65, v1
	v_add_f32_e64 v46, v46, -v56
	v_add_f32_e64 v47, v47, -v56
	v_add_f32_e32 v1, v66, v1
	v_mul_f32_e64 v68, v46, v46
	v_mul_f32_e64 v69, v47, v47
	v_add_f32_e32 v1, v67, v1
	v_add_f32_e64 v24, v24, -v56
	v_add_f32_e64 v25, v25, -v56
	v_add_f32_e32 v1, v68, v1
	v_mul_f32_e64 v70, v24, v24
	v_mul_f32_e64 v71, v25, v25
	v_add_f32_e32 v1, v69, v1
	v_add_f32_e64 v26, v26, -v56
	v_add_f32_e64 v27, v27, -v56
	v_add_f32_e32 v1, v70, v1
	v_mul_f32_e64 v72, v26, v26
	v_mul_f32_e64 v73, v27, v27
	v_add_f32_e32 v1, v71, v1
	v_add_f32_e64 v28, v28, -v56
	v_add_f32_e64 v29, v29, -v56
	v_add_f32_e32 v1, v72, v1
	v_mul_f32_e64 v74, v28, v28
	v_mul_f32_e64 v75, v29, v29
	v_add_f32_e32 v1, v73, v1
	v_add_f32_e64 v30, v30, -v56
	v_add_f32_e64 v31, v31, -v56
	v_add_f32_e32 v1, v74, v1
	v_mul_f32_e64 v76, v30, v30
	v_mul_f32_e64 v77, v31, v31
	v_add_f32_e32 v1, v75, v1
	v_add_f32_e64 v48, v48, -v56
	v_add_f32_e64 v49, v49, -v56
	v_add_f32_e32 v1, v76, v1
	v_mul_f32_e64 v78, v48, v48
	v_mul_f32_e64 v79, v49, v49
	v_add_f32_e32 v1, v77, v1
	v_add_f32_e64 v50, v50, -v56
	v_add_f32_e64 v51, v51, -v56
	v_add_f32_e32 v1, v78, v1
	v_mul_f32_e64 v80, v50, v50
	v_mul_f32_e64 v81, v51, v51
	v_add_f32_e32 v1, v79, v1
	v_add_f32_e64 v20, v20, -v56
	v_add_f32_e64 v21, v21, -v56
	v_add_f32_e32 v1, v80, v1
	v_mul_f32_e64 v82, v20, v20
	v_mul_f32_e64 v83, v21, v21
	v_add_f32_e32 v1, v81, v1
	v_add_f32_e64 v22, v22, -v56
	v_add_f32_e64 v23, v23, -v56
	v_add_f32_e32 v1, v82, v1
	v_mul_f32_e64 v84, v22, v22
	v_mul_f32_e64 v85, v23, v23
	v_add_f32_e32 v1, v83, v1
	v_add_f32_e64 v32, v32, -v56
	v_add_f32_e64 v33, v33, -v56
	v_add_f32_e32 v1, v84, v1
	v_mul_f32_e64 v86, v32, v32
	v_mul_f32_e64 v87, v33, v33
	v_add_f32_e32 v1, v85, v1
	v_add_f32_e64 v34, v34, -v56
	v_add_f32_e64 v35, v35, -v56
	v_add_f32_e32 v1, v86, v1
	v_mul_f32_e64 v56, v34, v34
	v_mul_f32_e64 v57, v35, v35
	v_add_f32_e32 v1, v87, v1
	v_add_f32_e32 v1, v56, v1
	v_add_f32_e32 v1, v57, v1
	ds_bpermute_b32 v56, v216, v1
	s_waitcnt lgkmcnt(0)
	v_add_f32_e32 v1, v1, v56
	ds_bpermute_b32 v56, v217, v1
	s_waitcnt lgkmcnt(0)
	v_add_f32_e32 v1, v1, v56
	ds_bpermute_b32 v56, v218, v1
	s_waitcnt lgkmcnt(0)
	v_add_f32_e32 v1, v1, v56
	ds_bpermute_b32 v56, v219, v1
	s_waitcnt lgkmcnt(0)
	v_add_f32_e32 v1, v1, v56
	ds_bpermute_b32 v58, v220, v1
	v_or_b32_e32 v56, 8, v0
	v_ashrrev_i32_e32 v57, 31, v56
	v_lshlrev_b64 v[56:57], 2, v[56:57]
	s_waitcnt lgkmcnt(0)
	v_add_f32_e32 v1, v1, v58
	ds_bpermute_b32 v60, v214, v1
	v_lshl_add_u64 v[58:59], s[6:7], 0, v[56:57]
	v_lshl_add_u64 v[56:57], s[8:9], 0, v[56:57]
	s_waitcnt lgkmcnt(0)
; DI unsigned pk2(float a, float b) { f32x2 v = {a, b}; bf2_t r = __builtin_convertvector(v, bf2_t); return __builtin_bit_cast(unsigned, r); }
; DI const float* modp(const Params& p, int layer, int v) { return (const float*)(p.ws + OFF_MOD) + (size_t)(layer * 2 + v) * 12288; }
; __device__ __forceinline__ void phase_expert(const Params& p, int layer, int row0) {
;     ...
;     const float rstd = rsqrtf(wave_sum(q) * (1.f / 2048.f) + LN_EPS);
;     const float* mdn = modp(p, 1, v);
; #pragma unroll
;     for (int c = 0; c < 2; ++c) {
; #pragma unroll
;       for (int q8 = 0; q8 < 2; ++q8) {
;         const int col = c * 1024 + lane2 * 16 + q8 * 8;
;         float o[8];
; #pragma unroll
;         for (int e = 0; e < 8; ++e) o[e] = (pre[c * 16 + q8 * 8 + e] - mu) * rstd * G[col + e] + B[col + e];
;         if (layer == 0) {
;           *(f32x4*)(XR + (size_t)row * LDF + col) = f32x4{o[0], o[1], o[2], o[3]};
;           *(f32x4*)(XR + (size_t)row * LDF + col + 4) = f32x4{o[4], o[5], o[6], o[7]};
;           float z[8];
; #pragma unroll
;           for (int e = 0; e < 8; ++e) z[e] = o[e] * (1.f + mdn[2048 + col + e]) + mdn[col + e];
;           *(u32x4*)(XMo + (size_t)row * LDX + col) = u32x4{pk2(z[0], z[1]), pk2(z[2], z[3]), pk2(z[4], z[5]), pk2(z[6], z[7])};
;         } else {
;           float* out = p.out + (size_t)(row - NCTX) * DM + col;
;           *(f32x4*)(out) = f32x4{o[0], o[1], o[2], o[3]};
;           *(f32x4*)(out + 4) = f32x4{o[4], o[5], o[6], o[7]};
;         }
	v_add_f32_e32 v1, v1, v60
	v_fmamk_f32 v1, v1, 0x3a000000, v224
	v_mul_f32_e32 v60, 0x4b800000, v1
	v_cmp_gt_f32_e32 vcc, s40, v1
	s_nop 1
	v_cndmask_b32_e32 v1, v1, v60, vcc
	v_rsq_f32_e32 v1, v1
	v_lshl_add_u64 v[60:61], s[0:1], 0, v[2:3]
	v_mul_f32_e32 v2, 0x45800000, v1
	v_cndmask_b32_e32 v62, v1, v2, vcc
	v_mul_f32_e64 v2, v40, v62
	v_mul_f32_e64 v3, v41, v62
	v_mul_f32_e64 v40, v42, v62
	v_mul_f32_e64 v41, v43, v62
	s_waitcnt vmcnt(0)
	v_fma_f32 v8, v8, v2, v16
	v_fma_f32 v9, v9, v3, v17
	v_fma_f32 v10, v10, v40, v18
	v_fma_f32 v11, v11, v41, v19
	v_mul_f32_e64 v2, v36, v62
	v_mul_f32_e64 v3, v37, v62
	v_mul_f32_e64 v16, v38, v62
	v_mul_f32_e64 v17, v39, v62
	v_fma_f32 v4, v4, v2, v12
	v_fma_f32 v5, v5, v3, v13
	v_fma_f32 v6, v6, v16, v14
	v_fma_f32 v7, v7, v17, v15
	global_store_dwordx4 v[60:61], v[8:11], off
	global_store_dwordx4 v[60:61], v[4:7], off offset:16
	global_load_dwordx4 v[2:5], v[56:57], off
	s_nop 0
	global_load_dwordx4 v[6:9], v[58:59], off
	global_load_dwordx4 v[10:13], v[58:59], off offset:16
	global_load_dwordx4 v[14:17], v[56:57], off offset:16
	v_add_u32_e32 v18, 0x402, v0
	v_add_co_u32_e32 v38, vcc, s38, v52
	v_mul_f32_e64 v42, v46, v62
	v_mul_f32_e64 v43, v47, v62
	v_mul_f32_e64 v44, v44, v62
	v_mul_f32_e64 v45, v45, v62
	v_ashrrev_i32_e32 v19, 31, v18
	v_addc_co_u32_e32 v39, vcc, 0, v53, vcc
	v_mul_f32_e64 v26, v26, v62
	v_mul_f32_e64 v27, v27, v62
	v_mul_f32_e64 v24, v24, v62
	v_mul_f32_e64 v25, v25, v62
	v_lshlrev_b64 v[18:19], 2, v[18:19]
	v_add_co_u32_e32 v40, vcc, s38, v54
	v_lshl_add_u64 v[36:37], s[6:7], 0, v[18:19]
	v_lshl_add_u64 v[18:19], s[8:9], 0, v[18:19]
	v_addc_co_u32_e32 v41, vcc, 0, v55, vcc
	v_add_u32_e32 v0, 0x40a, v0
	v_ashrrev_i32_e32 v1, 31, v0
	v_lshlrev_b64 v[0:1], 2, v[0:1]
	v_mul_f32_e64 v30, v30, v62
	v_mul_f32_e64 v31, v31, v62
	v_mul_f32_e64 v20, v20, v62
	v_mul_f32_e64 v21, v21, v62
	s_waitcnt vmcnt(2)
	v_fma_f32 v2, v6, v44, v2
	v_fma_f32 v3, v7, v45, v3
	v_fma_f32 v4, v8, v42, v4
	v_fma_f32 v5, v9, v43, v5
	s_waitcnt vmcnt(0)
	v_fma_f32 v6, v10, v24, v14
	v_fma_f32 v7, v11, v25, v15
	v_fma_f32 v8, v12, v26, v16
	v_fma_f32 v9, v13, v27, v17
	global_store_dwordx4 v[60:61], v[2:5], off offset:32
	global_store_dwordx4 v[60:61], v[6:9], off offset:48
	global_load_dwordx2 v[10:11], v[38:39], off
	global_load_dwordx2 v[12:13], v[40:41], off
	global_load_dwordx2 v[14:15], v[36:37], off offset:16
	s_nop 0
	global_load_dwordx4 v[2:5], v[36:37], off
	global_load_dwordx4 v[6:9], v[18:19], off
	global_load_dwordx2 v[16:17], v[18:19], off offset:16
	v_lshl_add_u64 v[18:19], s[6:7], 0, v[0:1]
	v_lshl_add_u64 v[24:25], s[8:9], 0, v[0:1]
	v_add_co_u32_e32 v36, vcc, s38, v60
	v_mul_f32_e64 v0, v28, v62
	v_mul_f32_e64 v1, v29, v62
	s_nop 0
	v_addc_co_u32_e32 v37, vcc, 0, v61, vcc
	v_mul_f32_e64 v28, v48, v62
	v_mul_f32_e64 v29, v49, v62
	v_mul_f32_e64 v42, v50, v62
	v_mul_f32_e64 v43, v51, v62
	v_lshl_add_u64 v[26:27], v[60:61], 0, s[18:19]
	v_cmp_lt_i32_e32 vcc, s41, v215
	s_or_b64 s[2:3], vcc, s[2:3]
	s_waitcnt vmcnt(4)
	v_fma_f32 v0, v10, v0, v12
	v_fma_f32 v1, v11, v1, v13
	s_waitcnt vmcnt(1)
	v_fma_f32 v2, v2, v30, v6
	v_fma_f32 v3, v3, v31, v7
	s_waitcnt vmcnt(0)
	v_fma_f32 v6, v14, v42, v16
	v_fma_f32 v7, v15, v43, v17
	v_fma_f32 v4, v4, v28, v8
	v_fma_f32 v5, v5, v29, v9
	global_store_dwordx4 v[36:37], v[0:3], off
	global_store_dwordx4 v[26:27], v[4:7], off offset:16
	global_load_dwordx2 v[8:9], v[38:39], off offset:32
	global_load_dwordx2 v[10:11], v[40:41], off offset:32
	global_load_dwordx2 v[12:13], v[18:19], off offset:16
	s_nop 0
	global_load_dwordx4 v[0:3], v[18:19], off
	global_load_dwordx4 v[4:7], v[24:25], off
	global_load_dwordx2 v[14:15], v[24:25], off offset:16
	v_mul_f32_e64 v18, v22, v62
	v_mul_f32_e64 v19, v23, v62
	v_mul_f32_e64 v22, v32, v62
	v_mul_f32_e64 v23, v33, v62
	v_mul_f32_e64 v24, v34, v62
	v_mul_f32_e64 v25, v35, v62
	v_lshl_add_u64 v[16:17], v[60:61], 0, s[24:25]
	s_waitcnt vmcnt(4)
	v_fma_f32 v8, v8, v20, v10
	v_fma_f32 v9, v9, v21, v11
	s_waitcnt vmcnt(1)
	v_fma_f32 v10, v0, v18, v4
	v_fma_f32 v11, v1, v19, v5
	s_waitcnt vmcnt(0)
	v_fma_f32 v4, v24, v12, v14
	v_fma_f32 v5, v25, v13, v15
	v_fma_f32 v2, v22, v2, v6
	v_fma_f32 v3, v23, v3, v7
	global_store_dwordx4 v[36:37], v[8:11], off offset:32
	global_store_dwordx4 v[16:17], v[2:5], off offset:16
	s_andn2_b64 exec, exec, s[2:3]
	s_cbranch_execnz .LBB0_2560
